# previous version plus removal of the x+0.0 packed adds hipcc kept in the bf16 unpack sequences (no-op on values)
# speedup vs baseline: 1.0041x; 1.0041x over previous
.LBB0_302:
	v_lshl_add_u32 v153, s25, 8, v145
	v_lshl_or_b32 v128, s66, 9, v151
	v_lshl_add_u32 v154, v153, 11, v128
	global_load_dwordx4 v[156:159], v154, s[20:21]
	v_or_b32_e32 v168, 64, v154
	global_load_dwordx4 v[160:163], v168, s[20:21]
	v_add_u32_e32 v169, 0x8000, v154
	global_load_dwordx4 v[132:135], v169, s[20:21]
	v_add_u32_e32 v155, 0x8040, v154
	global_load_dwordx4 v[128:131], v155, s[20:21]
	s_waitcnt vmcnt(0)
	v_lshlrev_b32_e32 v164, 16, v156
	v_and_b32_e32 v165, 0xffff0000, v156
	v_lshlrev_b32_e32 v156, 16, v157
	v_and_b32_e32 v157, 0xffff0000, v157
	v_lshlrev_b32_e32 v166, 16, v158
	v_and_b32_e32 v167, 0xffff0000, v158
	v_lshlrev_b32_e32 v158, 16, v159
	v_and_b32_e32 v159, 0xffff0000, v159
	v_pk_fma_f32 v[126:127], v[126:127], 0.5, v[156:157] op_sel_hi:[1,0,1]
	v_pk_fma_f32 v[124:125], v[124:125], 0.5, v[164:165] op_sel_hi:[1,0,1]
	v_pk_fma_f32 v[156:157], v[122:123], 0.5, v[158:159] op_sel_hi:[1,0,1]
	v_pk_fma_f32 v[158:159], v[120:121], 0.5, v[166:167] op_sel_hi:[1,0,1]
	v_cvt_pk_bf16_f32 v120, v124, v125
	v_cvt_pk_bf16_f32 v121, v126, v127
	s_nop 0
	v_cvt_pk_bf16_f32 v122, v158, v159
	v_cvt_pk_bf16_f32 v123, v156, v157
	global_store_dwordx4 v154, v[120:123], s[20:21]
	s_nop 1
	v_mul_f32_e32 v120, v125, v125
	v_mul_f32_e32 v121, v127, v127
	v_fmac_f32_e32 v120, v124, v124
	v_fmac_f32_e32 v121, v126, v126
	v_add_f32_e32 v120, v120, v121
	v_mul_f32_e32 v121, v159, v159
	v_fmac_f32_e32 v121, v158, v158
	v_add_f32_e32 v120, v121, v120
	v_mul_f32_e32 v121, v157, v157
	v_fmac_f32_e32 v121, v156, v156
	v_add_f32_e32 v156, v121, v120
	v_lshlrev_b32_e32 v120, 16, v160
	v_and_b32_e32 v121, 0xffff0000, v160
	v_lshlrev_b32_e32 v122, 16, v161
	v_and_b32_e32 v123, 0xffff0000, v161
	v_lshlrev_b32_e32 v124, 16, v162
	v_and_b32_e32 v125, 0xffff0000, v162
	v_lshlrev_b32_e32 v126, 16, v163
	v_and_b32_e32 v127, 0xffff0000, v163
	v_pk_fma_f32 v[118:119], v[118:119], 0.5, v[122:123] op_sel_hi:[1,0,1]
	v_pk_fma_f32 v[116:117], v[116:117], 0.5, v[120:121] op_sel_hi:[1,0,1]
	v_pk_fma_f32 v[122:123], v[112:113], 0.5, v[124:125] op_sel_hi:[1,0,1]
	v_cvt_pk_bf16_f32 v112, v116, v117
	v_cvt_pk_bf16_f32 v113, v118, v119
	v_pk_fma_f32 v[120:121], v[114:115], 0.5, v[126:127] op_sel_hi:[1,0,1]
	v_cvt_pk_bf16_f32 v114, v122, v123
	v_lshlrev_b32_e32 v126, 16, v132
	v_cvt_pk_bf16_f32 v115, v120, v121
	global_store_dwordx4 v168, v[112:115], s[20:21]
	v_and_b32_e32 v127, 0xffff0000, v132
	v_lshlrev_b32_e32 v132, 16, v133
	v_mul_f32_e32 v112, v117, v117
	v_mul_f32_e32 v113, v119, v119
	v_fmac_f32_e32 v112, v116, v116
	v_fmac_f32_e32 v113, v118, v118
	v_add_f32_e32 v112, v112, v113
	v_mul_f32_e32 v113, v123, v123
	v_fmac_f32_e32 v113, v122, v122
	v_add_f32_e32 v112, v113, v112
	v_mul_f32_e32 v113, v121, v121
	v_fmac_f32_e32 v113, v120, v120
	v_and_b32_e32 v114, 64, v212
	v_add_f32_e32 v112, v113, v112
	v_xor_b32_e32 v113, 16, v212
	v_add_u32_e32 v114, 64, v114
	v_cmp_lt_i32_e32 vcc, v113, v114
	v_add_f32_e32 v112, v156, v112
	v_and_b32_e32 v133, 0xffff0000, v133
	v_cndmask_b32_e32 v113, v212, v113, vcc
	v_lshlrev_b32_e32 v121, 2, v113
	ds_bpermute_b32 v113, v121, v112
	v_lshlrev_b32_e32 v156, 16, v134
	v_and_b32_e32 v157, 0xffff0000, v134
	v_add_u32_e32 v124, 0x10040, v154
	s_waitcnt lgkmcnt(0)
	v_add_f32_e32 v120, v112, v113
	v_xor_b32_e32 v112, 32, v212
	v_cmp_lt_i32_e32 vcc, v112, v114
	v_add_u32_e32 v125, 0x10000, v154
	s_nop 0
	v_cndmask_b32_e32 v112, v212, v112, vcc
	s_nop 0
	v_lshlrev_b32_e32 v134, 16, v135
	v_and_b32_e32 v135, 0xffff0000, v135
	v_lshlrev_b32_e32 v123, 2, v112
	global_load_dwordx4 v[112:115], v124, s[20:21]
	global_load_dwordx4 v[116:119], v125, s[20:21]
	v_pk_fma_f32 v[110:111], v[110:111], 0.5, v[132:133] op_sel_hi:[1,0,1]
	v_pk_fma_f32 v[108:109], v[108:109], 0.5, v[126:127] op_sel_hi:[1,0,1]
	v_pk_fma_f32 v[132:133], v[104:105], 0.5, v[156:157] op_sel_hi:[1,0,1]
	v_cvt_pk_bf16_f32 v104, v108, v109
	v_cvt_pk_bf16_f32 v105, v110, v111
	v_pk_fma_f32 v[126:127], v[106:107], 0.5, v[134:135] op_sel_hi:[1,0,1]
	v_cvt_pk_bf16_f32 v106, v132, v133
	ds_bpermute_b32 v122, v123, v120
	v_cvt_pk_bf16_f32 v107, v126, v127
	global_store_dwordx4 v169, v[104:107], s[20:21]
	s_nop 1
	v_mul_f32_e32 v104, v109, v109
	v_mul_f32_e32 v105, v111, v111
	v_fmac_f32_e32 v104, v108, v108
	v_fmac_f32_e32 v105, v110, v110
	v_add_f32_e32 v104, v104, v105
	v_mul_f32_e32 v105, v133, v133
	v_fmac_f32_e32 v105, v132, v132
	v_add_f32_e32 v104, v105, v104
	v_mul_f32_e32 v105, v127, v127
	v_fmac_f32_e32 v105, v126, v126
	v_add_f32_e32 v126, v105, v104
	v_lshlrev_b32_e32 v104, 16, v128
	v_and_b32_e32 v105, 0xffff0000, v128
	v_lshlrev_b32_e32 v106, 16, v129
	v_and_b32_e32 v107, 0xffff0000, v129
	v_lshlrev_b32_e32 v108, 16, v130
	v_and_b32_e32 v109, 0xffff0000, v130
	v_lshlrev_b32_e32 v110, 16, v131
	v_and_b32_e32 v111, 0xffff0000, v131
	v_pk_fma_f32 v[102:103], v[102:103], 0.5, v[106:107] op_sel_hi:[1,0,1]
	v_pk_fma_f32 v[100:101], v[100:101], 0.5, v[104:105] op_sel_hi:[1,0,1]
	v_pk_fma_f32 v[106:107], v[96:97], 0.5, v[108:109] op_sel_hi:[1,0,1]
	v_cvt_pk_bf16_f32 v96, v100, v101
	v_cvt_pk_bf16_f32 v97, v102, v103
	v_pk_fma_f32 v[104:105], v[98:99], 0.5, v[110:111] op_sel_hi:[1,0,1]
	v_cvt_pk_bf16_f32 v98, v106, v107
	s_waitcnt vmcnt(1)
	v_lshlrev_b32_e32 v108, 16, v116
	v_cvt_pk_bf16_f32 v99, v104, v105
	global_store_dwordx4 v155, v[96:99], s[20:21]
	v_and_b32_e32 v109, 0xffff0000, v116
	v_lshlrev_b32_e32 v110, 16, v117
	v_mul_f32_e32 v96, v101, v101
	v_mul_f32_e32 v97, v103, v103
	v_fmac_f32_e32 v96, v100, v100
	v_fmac_f32_e32 v97, v102, v102
	v_add_f32_e32 v96, v96, v97
	v_mul_f32_e32 v97, v107, v107
	v_fmac_f32_e32 v97, v106, v106
	v_add_f32_e32 v96, v97, v96
	v_mul_f32_e32 v97, v105, v105
	v_fmac_f32_e32 v97, v104, v104
	v_add_f32_e32 v96, v97, v96
	v_add_f32_e32 v96, v96, v126
	ds_bpermute_b32 v97, v121, v96
	v_add_u32_e32 v102, 0x18040, v154
	v_add_u32_e32 v103, 0x18000, v154
	global_load_dwordx4 v[104:107], v103, s[20:21]
	v_and_b32_e32 v111, 0xffff0000, v117
	s_waitcnt lgkmcnt(0)
	v_add_f32_e32 v100, v96, v97
	global_load_dwordx4 v[96:99], v102, s[20:21]
	v_lshlrev_b32_e32 v116, 16, v118
	v_and_b32_e32 v117, 0xffff0000, v118
	v_lshlrev_b32_e32 v118, 16, v119
	v_and_b32_e32 v119, 0xffff0000, v119
	v_pk_fma_f32 v[94:95], v[94:95], 0.5, v[110:111] op_sel_hi:[1,0,1]
	v_pk_fma_f32 v[92:93], v[92:93], 0.5, v[108:109] op_sel_hi:[1,0,1]
	v_pk_fma_f32 v[110:111], v[88:89], 0.5, v[116:117] op_sel_hi:[1,0,1]
	v_cvt_pk_bf16_f32 v88, v92, v93
	v_cvt_pk_bf16_f32 v89, v94, v95
	v_pk_fma_f32 v[108:109], v[90:91], 0.5, v[118:119] op_sel_hi:[1,0,1]
	v_cvt_pk_bf16_f32 v90, v110, v111
	ds_bpermute_b32 v101, v123, v100
	v_cvt_pk_bf16_f32 v91, v108, v109
	global_store_dwordx4 v125, v[88:91], s[20:21]
	s_nop 1
	v_mul_f32_e32 v88, v93, v93
	v_mul_f32_e32 v89, v95, v95
	v_fmac_f32_e32 v88, v92, v92
	v_fmac_f32_e32 v89, v94, v94
	v_add_f32_e32 v88, v88, v89
	v_mul_f32_e32 v89, v111, v111
	v_fmac_f32_e32 v89, v110, v110
	v_add_f32_e32 v88, v89, v88
	v_mul_f32_e32 v89, v109, v109
	v_fmac_f32_e32 v89, v108, v108
	v_add_f32_e32 v108, v89, v88
	v_lshlrev_b32_e32 v88, 16, v112
	v_and_b32_e32 v89, 0xffff0000, v112
	v_lshlrev_b32_e32 v90, 16, v113
	v_and_b32_e32 v91, 0xffff0000, v113
	v_lshlrev_b32_e32 v92, 16, v114
	v_and_b32_e32 v93, 0xffff0000, v114
	v_lshlrev_b32_e32 v94, 16, v115
	v_and_b32_e32 v95, 0xffff0000, v115
	v_pk_fma_f32 v[86:87], v[86:87], 0.5, v[90:91] op_sel_hi:[1,0,1]
	v_pk_fma_f32 v[84:85], v[84:85], 0.5, v[88:89] op_sel_hi:[1,0,1]
	v_pk_fma_f32 v[90:91], v[80:81], 0.5, v[92:93] op_sel_hi:[1,0,1]
	v_cvt_pk_bf16_f32 v80, v84, v85
	v_cvt_pk_bf16_f32 v81, v86, v87
	v_pk_fma_f32 v[88:89], v[82:83], 0.5, v[94:95] op_sel_hi:[1,0,1]
	v_cvt_pk_bf16_f32 v82, v90, v91
	v_add_u32_e32 v109, 0x40000, v154
	v_cvt_pk_bf16_f32 v83, v88, v89
	global_store_dwordx4 v124, v[80:83], s[20:21]
	s_waitcnt vmcnt(3)
	v_lshlrev_b32_e32 v92, 16, v105
	v_mul_f32_e32 v80, v85, v85
	v_mul_f32_e32 v81, v87, v87
	v_fmac_f32_e32 v80, v84, v84
	v_fmac_f32_e32 v81, v86, v86
	v_add_f32_e32 v80, v80, v81
	v_mul_f32_e32 v81, v91, v91
	v_fmac_f32_e32 v81, v90, v90
	v_add_f32_e32 v80, v81, v80
	v_mul_f32_e32 v81, v89, v89
	v_fmac_f32_e32 v81, v88, v88
	v_add_f32_e32 v80, v81, v80
	v_add_f32_e32 v80, v80, v108
	ds_bpermute_b32 v81, v121, v80
	v_lshlrev_b32_e32 v90, 16, v104
	v_and_b32_e32 v91, 0xffff0000, v104
	v_and_b32_e32 v93, 0xffff0000, v105
	v_lshlrev_b32_e32 v94, 16, v106
	v_and_b32_e32 v95, 0xffff0000, v106
	v_add_u32_e32 v108, 0x40040, v154
	v_lshlrev_b32_e32 v104, 16, v107
	v_and_b32_e32 v105, 0xffff0000, v107
	s_waitcnt lgkmcnt(0)
	v_add_f32_e32 v88, v80, v81
	global_load_dwordx4 v[80:83], v108, s[20:21]
	global_load_dwordx4 v[84:87], v109, s[20:21]
	v_pk_fma_f32 v[78:79], v[78:79], 0.5, v[92:93] op_sel_hi:[1,0,1]
	v_pk_fma_f32 v[76:77], v[76:77], 0.5, v[90:91] op_sel_hi:[1,0,1]
	v_pk_fma_f32 v[92:93], v[72:73], 0.5, v[94:95] op_sel_hi:[1,0,1]
	v_cvt_pk_bf16_f32 v72, v76, v77
	v_cvt_pk_bf16_f32 v73, v78, v79
	v_pk_fma_f32 v[90:91], v[74:75], 0.5, v[104:105] op_sel_hi:[1,0,1]
	v_cvt_pk_bf16_f32 v74, v92, v93
	ds_bpermute_b32 v89, v123, v88
	v_cvt_pk_bf16_f32 v75, v90, v91
	global_store_dwordx4 v103, v[72:75], s[20:21]
	s_nop 1
	v_mul_f32_e32 v72, v77, v77
	v_mul_f32_e32 v73, v79, v79
	v_fmac_f32_e32 v72, v76, v76
	v_fmac_f32_e32 v73, v78, v78
	v_add_f32_e32 v72, v72, v73
	v_mul_f32_e32 v73, v93, v93
	v_fmac_f32_e32 v73, v92, v92
	v_add_f32_e32 v72, v73, v72
	v_mul_f32_e32 v73, v91, v91
	v_fmac_f32_e32 v73, v90, v90
	v_add_f32_e32 v90, v73, v72
	s_waitcnt vmcnt(5)
	v_lshlrev_b32_e32 v72, 16, v96
	v_and_b32_e32 v73, 0xffff0000, v96
	v_lshlrev_b32_e32 v74, 16, v97
	v_and_b32_e32 v75, 0xffff0000, v97
	v_lshlrev_b32_e32 v76, 16, v98
	v_and_b32_e32 v77, 0xffff0000, v98
	v_lshlrev_b32_e32 v78, 16, v99
	v_and_b32_e32 v79, 0xffff0000, v99
	v_pk_fma_f32 v[70:71], v[70:71], 0.5, v[74:75] op_sel_hi:[1,0,1]
	v_pk_fma_f32 v[68:69], v[68:69], 0.5, v[72:73] op_sel_hi:[1,0,1]
	v_pk_fma_f32 v[74:75], v[64:65], 0.5, v[76:77] op_sel_hi:[1,0,1]
	v_cvt_pk_bf16_f32 v64, v68, v69
	v_cvt_pk_bf16_f32 v65, v70, v71
	v_pk_fma_f32 v[72:73], v[66:67], 0.5, v[78:79] op_sel_hi:[1,0,1]
	v_cvt_pk_bf16_f32 v66, v74, v75
	v_add_u32_e32 v91, 0x48000, v154
	v_cvt_pk_bf16_f32 v67, v72, v73
	global_store_dwordx4 v102, v[64:67], s[20:21]
	s_waitcnt vmcnt(2)
	v_lshlrev_b32_e32 v76, 16, v85
	v_mul_f32_e32 v64, v69, v69
	v_mul_f32_e32 v65, v71, v71
	v_fmac_f32_e32 v64, v68, v68
	v_fmac_f32_e32 v65, v70, v70
	v_add_f32_e32 v64, v64, v65
	v_mul_f32_e32 v65, v75, v75
	v_fmac_f32_e32 v65, v74, v74
	v_add_f32_e32 v64, v65, v64
	v_mul_f32_e32 v65, v73, v73
	v_fmac_f32_e32 v65, v72, v72
	v_add_f32_e32 v64, v65, v64
	v_add_f32_e32 v64, v64, v90
	ds_bpermute_b32 v65, v121, v64
	v_add_u32_e32 v90, 0x48040, v154
	global_load_dwordx4 v[70:73], v91, s[20:21]
	v_lshlrev_b32_e32 v74, 16, v84
	v_and_b32_e32 v75, 0xffff0000, v84
	s_waitcnt lgkmcnt(0)
	v_add_f32_e32 v68, v64, v65
	global_load_dwordx4 v[64:67], v90, s[20:21]
	v_and_b32_e32 v77, 0xffff0000, v85
	v_lshlrev_b32_e32 v78, 16, v86
	v_and_b32_e32 v79, 0xffff0000, v86
	v_lshlrev_b32_e32 v84, 16, v87
	v_and_b32_e32 v85, 0xffff0000, v87
	v_pk_fma_f32 v[62:63], v[62:63], 0.5, v[76:77] op_sel_hi:[1,0,1]
	v_pk_fma_f32 v[60:61], v[60:61], 0.5, v[74:75] op_sel_hi:[1,0,1]
	v_pk_fma_f32 v[76:77], v[56:57], 0.5, v[78:79] op_sel_hi:[1,0,1]
	v_cvt_pk_bf16_f32 v56, v60, v61
	v_cvt_pk_bf16_f32 v57, v62, v63
	v_pk_fma_f32 v[74:75], v[58:59], 0.5, v[84:85] op_sel_hi:[1,0,1]
	v_cvt_pk_bf16_f32 v58, v76, v77
	ds_bpermute_b32 v69, v123, v68
	v_cvt_pk_bf16_f32 v59, v74, v75
	global_store_dwordx4 v109, v[56:59], s[20:21]
	s_nop 1
	v_mul_f32_e32 v56, v61, v61
	v_mul_f32_e32 v57, v63, v63
	v_fmac_f32_e32 v56, v60, v60
	v_fmac_f32_e32 v57, v62, v62
	v_add_f32_e32 v56, v56, v57
	v_mul_f32_e32 v57, v77, v77
	v_fmac_f32_e32 v57, v76, v76
	v_add_f32_e32 v56, v57, v56
	v_mul_f32_e32 v57, v75, v75
	v_fmac_f32_e32 v57, v74, v74
	v_add_f32_e32 v74, v57, v56
	v_lshlrev_b32_e32 v56, 16, v80
	v_and_b32_e32 v57, 0xffff0000, v80
	v_lshlrev_b32_e32 v58, 16, v81
	v_and_b32_e32 v59, 0xffff0000, v81
	v_lshlrev_b32_e32 v60, 16, v82
	v_and_b32_e32 v61, 0xffff0000, v82
	v_lshlrev_b32_e32 v62, 16, v83
	v_and_b32_e32 v63, 0xffff0000, v83
	v_pk_fma_f32 v[54:55], v[54:55], 0.5, v[58:59] op_sel_hi:[1,0,1]
	v_pk_fma_f32 v[52:53], v[52:53], 0.5, v[56:57] op_sel_hi:[1,0,1]
	v_pk_fma_f32 v[58:59], v[48:49], 0.5, v[60:61] op_sel_hi:[1,0,1]
	v_cvt_pk_bf16_f32 v48, v52, v53
	v_cvt_pk_bf16_f32 v49, v54, v55
	v_pk_fma_f32 v[56:57], v[50:51], 0.5, v[62:63] op_sel_hi:[1,0,1]
	v_cvt_pk_bf16_f32 v50, v58, v59
	v_add_u32_e32 v75, 0x50000, v154
	v_cvt_pk_bf16_f32 v51, v56, v57
	global_store_dwordx4 v108, v[48:51], s[20:21]
	s_waitcnt vmcnt(3)
	v_lshlrev_b32_e32 v60, 16, v71
	v_mul_f32_e32 v48, v53, v53
	v_mul_f32_e32 v49, v55, v55
	v_fmac_f32_e32 v48, v52, v52
	v_fmac_f32_e32 v49, v54, v54
	v_add_f32_e32 v48, v48, v49
	v_mul_f32_e32 v49, v59, v59
	v_fmac_f32_e32 v49, v58, v58
	v_add_f32_e32 v48, v49, v48
	v_mul_f32_e32 v49, v57, v57
	v_fmac_f32_e32 v49, v56, v56
	v_add_f32_e32 v48, v49, v48
	v_add_f32_e32 v48, v48, v74
	ds_bpermute_b32 v49, v121, v48
	v_lshlrev_b32_e32 v58, 16, v70
	v_and_b32_e32 v59, 0xffff0000, v70
	v_and_b32_e32 v61, 0xffff0000, v71
	v_lshlrev_b32_e32 v62, 16, v72
	v_and_b32_e32 v63, 0xffff0000, v72
	v_add_u32_e32 v74, 0x50040, v154
	v_lshlrev_b32_e32 v70, 16, v73
	v_and_b32_e32 v71, 0xffff0000, v73
	s_waitcnt lgkmcnt(0)
	v_add_f32_e32 v52, v48, v49
	global_load_dwordx4 v[48:51], v74, s[20:21]
	global_load_dwordx4 v[54:57], v75, s[20:21]
	v_pk_fma_f32 v[46:47], v[46:47], 0.5, v[60:61] op_sel_hi:[1,0,1]
	v_pk_fma_f32 v[44:45], v[44:45], 0.5, v[58:59] op_sel_hi:[1,0,1]
	v_pk_fma_f32 v[60:61], v[40:41], 0.5, v[62:63] op_sel_hi:[1,0,1]
	v_cvt_pk_bf16_f32 v40, v44, v45
	v_cvt_pk_bf16_f32 v41, v46, v47
	v_pk_fma_f32 v[58:59], v[42:43], 0.5, v[70:71] op_sel_hi:[1,0,1]
	v_cvt_pk_bf16_f32 v42, v60, v61
	ds_bpermute_b32 v53, v123, v52
	v_cvt_pk_bf16_f32 v43, v58, v59
	global_store_dwordx4 v91, v[40:43], s[20:21]
	s_nop 1
	v_mul_f32_e32 v40, v45, v45
	v_mul_f32_e32 v41, v47, v47
	v_fmac_f32_e32 v40, v44, v44
	v_fmac_f32_e32 v41, v46, v46
	v_add_f32_e32 v40, v40, v41
	v_mul_f32_e32 v41, v61, v61
	v_fmac_f32_e32 v41, v60, v60
	v_add_f32_e32 v40, v41, v40
	v_mul_f32_e32 v41, v59, v59
	v_fmac_f32_e32 v41, v58, v58
	v_add_f32_e32 v58, v41, v40
	s_waitcnt vmcnt(5)
	v_lshlrev_b32_e32 v40, 16, v64
	v_and_b32_e32 v41, 0xffff0000, v64
	v_lshlrev_b32_e32 v42, 16, v65
	v_and_b32_e32 v43, 0xffff0000, v65
	v_lshlrev_b32_e32 v44, 16, v66
	v_and_b32_e32 v45, 0xffff0000, v66
	v_lshlrev_b32_e32 v46, 16, v67
	v_and_b32_e32 v47, 0xffff0000, v67
	v_pk_fma_f32 v[38:39], v[38:39], 0.5, v[42:43] op_sel_hi:[1,0,1]
	v_pk_fma_f32 v[36:37], v[36:37], 0.5, v[40:41] op_sel_hi:[1,0,1]
	v_pk_fma_f32 v[42:43], v[32:33], 0.5, v[44:45] op_sel_hi:[1,0,1]
	v_cvt_pk_bf16_f32 v32, v36, v37
	v_cvt_pk_bf16_f32 v33, v38, v39
	v_pk_fma_f32 v[40:41], v[34:35], 0.5, v[46:47] op_sel_hi:[1,0,1]
	v_cvt_pk_bf16_f32 v34, v42, v43
	v_add_u32_e32 v59, 0x58000, v154
	v_cvt_pk_bf16_f32 v35, v40, v41
	global_store_dwordx4 v90, v[32:35], s[20:21]
	s_waitcnt vmcnt(2)
	v_lshlrev_b32_e32 v44, 16, v55
	v_mul_f32_e32 v32, v37, v37
	v_mul_f32_e32 v33, v39, v39
	v_fmac_f32_e32 v32, v36, v36
	v_fmac_f32_e32 v33, v38, v38
	v_add_f32_e32 v32, v32, v33
	v_mul_f32_e32 v33, v43, v43
	v_fmac_f32_e32 v33, v42, v42
	v_add_f32_e32 v32, v33, v32
	v_mul_f32_e32 v33, v41, v41
	v_fmac_f32_e32 v33, v40, v40
	v_add_f32_e32 v32, v33, v32
	v_add_f32_e32 v32, v32, v58
	ds_bpermute_b32 v33, v121, v32
	v_add_u32_e32 v58, 0x58040, v154
	global_load_dwordx4 v[38:41], v59, s[20:21]
	v_lshlrev_b32_e32 v42, 16, v54
	v_and_b32_e32 v43, 0xffff0000, v54
	s_waitcnt lgkmcnt(0)
	v_add_f32_e32 v36, v32, v33
	global_load_dwordx4 v[32:35], v58, s[20:21]
	v_and_b32_e32 v45, 0xffff0000, v55
	v_lshlrev_b32_e32 v46, 16, v56
	v_and_b32_e32 v47, 0xffff0000, v56
	v_lshlrev_b32_e32 v54, 16, v57
	v_and_b32_e32 v55, 0xffff0000, v57
	v_pk_fma_f32 v[30:31], v[30:31], 0.5, v[44:45] op_sel_hi:[1,0,1]
	v_pk_fma_f32 v[28:29], v[28:29], 0.5, v[42:43] op_sel_hi:[1,0,1]
	v_pk_fma_f32 v[44:45], v[24:25], 0.5, v[46:47] op_sel_hi:[1,0,1]
	v_cvt_pk_bf16_f32 v24, v28, v29
	v_cvt_pk_bf16_f32 v25, v30, v31
	v_pk_fma_f32 v[42:43], v[26:27], 0.5, v[54:55] op_sel_hi:[1,0,1]
	v_cvt_pk_bf16_f32 v26, v44, v45
	ds_bpermute_b32 v37, v123, v36
	v_cvt_pk_bf16_f32 v27, v42, v43
	global_store_dwordx4 v75, v[24:27], s[20:21]
	s_nop 1
	v_mul_f32_e32 v24, v29, v29
	v_mul_f32_e32 v25, v31, v31
	v_fmac_f32_e32 v24, v28, v28
	v_fmac_f32_e32 v25, v30, v30
	v_add_f32_e32 v24, v24, v25
	v_mul_f32_e32 v25, v45, v45
	v_fmac_f32_e32 v25, v44, v44
	v_add_f32_e32 v24, v25, v24
	v_mul_f32_e32 v25, v43, v43
	v_fmac_f32_e32 v25, v42, v42
	v_add_f32_e32 v42, v25, v24
	v_lshlrev_b32_e32 v24, 16, v48
	v_and_b32_e32 v25, 0xffff0000, v48
	v_lshlrev_b32_e32 v26, 16, v49
	v_and_b32_e32 v27, 0xffff0000, v49
	v_lshlrev_b32_e32 v28, 16, v50
	v_and_b32_e32 v29, 0xffff0000, v50
	v_lshlrev_b32_e32 v30, 16, v51
	v_and_b32_e32 v31, 0xffff0000, v51
	v_pk_fma_f32 v[22:23], v[22:23], 0.5, v[26:27] op_sel_hi:[1,0,1]
	v_pk_fma_f32 v[20:21], v[20:21], 0.5, v[24:25] op_sel_hi:[1,0,1]
	v_pk_fma_f32 v[26:27], v[16:17], 0.5, v[28:29] op_sel_hi:[1,0,1]
	v_cvt_pk_bf16_f32 v16, v20, v21
	v_cvt_pk_bf16_f32 v17, v22, v23
	v_pk_fma_f32 v[24:25], v[18:19], 0.5, v[30:31] op_sel_hi:[1,0,1]
	v_cvt_pk_bf16_f32 v18, v26, v27
	s_nop 0
	v_cvt_pk_bf16_f32 v19, v24, v25
	global_store_dwordx4 v74, v[16:19], s[20:21]
	s_nop 1
	v_mul_f32_e32 v16, v21, v21
	v_mul_f32_e32 v17, v23, v23
	v_fmac_f32_e32 v16, v20, v20
	v_fmac_f32_e32 v17, v22, v22
	v_add_f32_e32 v16, v16, v17
	v_mul_f32_e32 v17, v27, v27
	v_fmac_f32_e32 v17, v26, v26
	v_add_f32_e32 v16, v17, v16
	v_mul_f32_e32 v17, v25, v25
	v_fmac_f32_e32 v17, v24, v24
	v_add_f32_e32 v16, v17, v16
	v_add_f32_e32 v16, v16, v42
	ds_bpermute_b32 v17, v121, v16
	s_waitcnt lgkmcnt(0)
	v_add_f32_e32 v16, v16, v17
	s_waitcnt vmcnt(3)
	v_lshlrev_b32_e32 v18, 16, v38
	v_and_b32_e32 v19, 0xffff0000, v38
	v_lshlrev_b32_e32 v20, 16, v39
	v_and_b32_e32 v21, 0xffff0000, v39
	v_lshlrev_b32_e32 v22, 16, v40
	v_and_b32_e32 v23, 0xffff0000, v40
	v_lshlrev_b32_e32 v24, 16, v41
	v_and_b32_e32 v25, 0xffff0000, v41
	v_pk_fma_f32 v[14:15], v[14:15], 0.5, v[20:21] op_sel_hi:[1,0,1]
	v_pk_fma_f32 v[12:13], v[12:13], 0.5, v[18:19] op_sel_hi:[1,0,1]
	v_pk_fma_f32 v[20:21], v[8:9], 0.5, v[22:23] op_sel_hi:[1,0,1]
	v_cvt_pk_bf16_f32 v8, v12, v13
	v_cvt_pk_bf16_f32 v9, v14, v15
	v_pk_fma_f32 v[18:19], v[10:11], 0.5, v[24:25] op_sel_hi:[1,0,1]
	v_cvt_pk_bf16_f32 v10, v20, v21
	ds_bpermute_b32 v17, v123, v16
	v_cvt_pk_bf16_f32 v11, v18, v19
	global_store_dwordx4 v59, v[8:11], s[20:21]
	s_nop 1
	v_mul_f32_e32 v8, v13, v13
	v_mul_f32_e32 v9, v15, v15
	v_fmac_f32_e32 v8, v12, v12
	v_fmac_f32_e32 v9, v14, v14
	v_add_f32_e32 v8, v8, v9
	v_mul_f32_e32 v9, v21, v21
	v_fmac_f32_e32 v9, v20, v20
	v_add_f32_e32 v8, v9, v8
	v_mul_f32_e32 v9, v19, v19
	v_fmac_f32_e32 v9, v18, v18
	v_add_f32_e32 v18, v9, v8
	s_waitcnt vmcnt(3)
	v_lshlrev_b32_e32 v8, 16, v32
	v_and_b32_e32 v9, 0xffff0000, v32
	v_lshlrev_b32_e32 v10, 16, v33
	v_and_b32_e32 v11, 0xffff0000, v33
	v_lshlrev_b32_e32 v12, 16, v34
	v_and_b32_e32 v13, 0xffff0000, v34
	v_lshlrev_b32_e32 v14, 16, v35
	v_and_b32_e32 v15, 0xffff0000, v35
	v_pk_fma_f32 v[6:7], v[6:7], 0.5, v[10:11] op_sel_hi:[1,0,1]
	v_pk_fma_f32 v[4:5], v[4:5], 0.5, v[8:9] op_sel_hi:[1,0,1]
	v_pk_fma_f32 v[10:11], v[0:1], 0.5, v[12:13] op_sel_hi:[1,0,1]
	v_cvt_pk_bf16_f32 v0, v4, v5
	v_cvt_pk_bf16_f32 v1, v6, v7
	v_pk_fma_f32 v[8:9], v[2:3], 0.5, v[14:15] op_sel_hi:[1,0,1]
	v_cvt_pk_bf16_f32 v2, v10, v11
	s_nop 0
	v_cvt_pk_bf16_f32 v3, v8, v9
	global_store_dwordx4 v58, v[0:3], s[20:21]
	s_nop 1
	v_mul_f32_e32 v0, v5, v5
	v_mul_f32_e32 v1, v7, v7
	v_fmac_f32_e32 v0, v4, v4
	v_fmac_f32_e32 v1, v6, v6
	v_add_f32_e32 v0, v0, v1
	v_mul_f32_e32 v1, v11, v11
	v_fmac_f32_e32 v1, v10, v10
	v_add_f32_e32 v0, v1, v0
	v_mul_f32_e32 v1, v9, v9
	v_fmac_f32_e32 v1, v8, v8
	v_add_f32_e32 v0, v1, v0
	v_add_f32_e32 v0, v0, v18
	ds_bpermute_b32 v1, v121, v0
	s_waitcnt lgkmcnt(0)
	v_add_f32_e32 v0, v0, v1
	ds_bpermute_b32 v1, v123, v0
	s_and_saveexec_b64 s[56:57], s[42:43]
	s_cbranch_execz .LBB0_304
	s_lshl_b32 s25, s66, 4
	s_or_b32 s25, s25, s84
	v_add_f32_e32 v8, v120, v122
	s_waitcnt lgkmcnt(0)
	v_add_f32_e32 v0, v0, v1
	v_lshl_add_u32 v1, v153, 6, s25
	v_add_f32_e32 v7, v100, v101
	global_store_dword v1, v8, s[74:75]
	v_add_u32_e32 v8, 0x400, v1
	v_add_f32_e32 v6, v88, v89
	global_store_dword v8, v7, s[74:75]
	v_add_u32_e32 v7, 0x800, v1
	v_add_f32_e32 v5, v68, v69
	global_store_dword v7, v6, s[74:75]
	v_add_u32_e32 v6, 0xc00, v1
	v_add_f32_e32 v4, v52, v53
	global_store_dword v6, v5, s[74:75]
	v_add_u32_e32 v5, 0x2000, v1
	v_add_f32_e32 v3, v36, v37
	global_store_dword v5, v4, s[74:75]
	v_add_u32_e32 v4, 0x2400, v1
	v_add_f32_e32 v2, v16, v17
	global_store_dword v4, v3, s[74:75]
	v_add_u32_e32 v3, 0x2800, v1
	v_add_u32_e32 v1, 0x2c00, v1
	global_store_dword v3, v2, s[74:75]
	global_store_dword v1, v0, s[74:75]

.LBB0_549:
	s_add_i32 s24, s48, s46
	s_add_i32 s44, s24, 0xffc0
	s_ashr_i32 s45, s44, 31
	s_add_i32 s25, s47, s46
	s_lshl_b64 s[26:27], s[44:45], 10
	v_lshl_add_u64 v[88:89], v[108:109], 0, s[26:27]
	s_cmp_gt_i32 s25, 0
	global_load_dwordx4 v[92:95], v[88:89], off
	v_lshl_add_u64 v[88:89], v[110:111], 0, s[26:27]
	s_cselect_b64 s[26:27], -1, 0
	s_cmp_lg_u64 s[26:27], 0
	s_subb_u32 s26, s44, 0
	s_ashr_i32 s27, s26, 31
	s_lshl_b64 s[26:27], s[26:27], 10
	v_lshl_add_u64 v[96:97], v[108:109], 0, s[26:27]
	global_load_dwordx4 v[88:91], v[88:89], off
	s_cmpk_lt_i32 s25, 0x7ff
	global_load_dwordx4 v[100:103], v[96:97], off
	s_cselect_b64 s[26:27], -1, 0
	s_cmp_lg_u64 s[26:27], 0
	s_addc_u32 s26, s24, 0xffc0
	s_ashr_i32 s27, s26, 31
	s_lshl_b64 s[26:27], s[26:27], 10
	s_cmp_lg_u32 s25, 0
	v_lshl_add_u64 v[96:97], v[108:109], 0, s[26:27]
	s_cselect_b64 vcc, -1, 0
	global_load_dwordx4 v[96:99], v[96:97], off
	s_mov_b32 s28, 0x3b000000
	s_waitcnt vmcnt(3)
	v_and_b32_e32 v131, 0xffff0000, v94
	s_waitcnt vmcnt(2)
	v_lshlrev_b32_e32 v136, 16, v88
	v_and_b32_e32 v137, 0xffff0000, v88
	s_waitcnt vmcnt(1)
	v_cndmask_b32_e32 v117, 0, v103, vcc
	v_cndmask_b32_e32 v128, 0, v102, vcc
	v_cndmask_b32_e32 v129, 0, v101, vcc
	v_cndmask_b32_e32 v130, 0, v100, vcc
	ds_read_b128 v[104:107], v116
	ds_read_b128 v[100:103], v116 offset:16
	v_lshlrev_b32_e32 v88, 16, v89
	v_and_b32_e32 v89, 0xffff0000, v89
	s_waitcnt lgkmcnt(1)
	v_mov_b32_e32 v114, v104
	s_waitcnt lgkmcnt(0)
	v_mov_b32_e32 v115, v100
	v_mov_b32_e32 v118, v105
	v_mov_b32_e32 v119, v101
	v_pk_add_f32 v[120:121], v[114:115], v[118:119]
	v_mov_b32_e32 v122, v106
	v_mov_b32_e32 v123, v102
	v_mov_b32_e32 v124, v107
	v_mov_b32_e32 v125, v103
	v_pk_mul_f32 v[118:119], v[118:119], v[118:119]
	v_pk_add_f32 v[126:127], v[122:123], v[124:125]
	v_pk_fma_f32 v[114:115], v[114:115], v[114:115], v[118:119]
	v_pk_mul_f32 v[118:119], v[124:125], v[124:125]
	v_pk_add_f32 v[120:121], v[120:121], v[126:127]
	v_pk_fma_f32 v[118:119], v[122:123], v[122:123], v[118:119]
	v_add_f32_e32 v120, v120, v121
	v_pk_add_f32 v[114:115], v[114:115], v[118:119]
	v_mov_b32_e32 v118, 0
	v_add_f32_e32 v114, v114, v115
	v_add_f32_dpp v115, v120, v120 quad_perm:[1,0,3,2] row_mask:0xf bank_mask:0xf bound_ctrl:1
	v_lshlrev_b32_e32 v126, 16, v117
	v_add_f32_dpp v114, v114, v114 quad_perm:[1,0,3,2] row_mask:0xf bank_mask:0xf bound_ctrl:1
	v_add_f32_dpp v115, v115, v115 quad_perm:[2,3,0,1] row_mask:0xf bank_mask:0xf bound_ctrl:1
	v_and_b32_e32 v127, 0xffff0000, v117
	v_add_f32_dpp v114, v114, v114 quad_perm:[2,3,0,1] row_mask:0xf bank_mask:0xf bound_ctrl:1
	v_add_f32_dpp v115, v115, v115 row_shr:4 row_mask:0xf bank_mask:0xf bound_ctrl:1
	v_lshlrev_b32_e32 v120, 16, v130
	v_add_f32_dpp v114, v114, v114 row_shr:4 row_mask:0xf bank_mask:0xf bound_ctrl:1
	v_add_f32_dpp v115, v115, v115 row_shr:8 row_mask:0xf bank_mask:0xf bound_ctrl:1
	v_and_b32_e32 v121, 0xffff0000, v130
	v_add_f32_dpp v114, v114, v114 row_shr:8 row_mask:0xf bank_mask:0xf bound_ctrl:1
	v_mov_b32_dpp v118, v115 row_bcast:15 row_mask:0xa bank_mask:0xf
	v_add_f32_e32 v115, v115, v118
	v_mov_b32_e32 v118, 0
	v_lshlrev_b32_e32 v122, 16, v129
	v_and_b32_e32 v123, 0xffff0000, v129
	v_mov_b32_dpp v118, v115 row_bcast:31 row_mask:0xc bank_mask:0xf
	v_add_f32_e32 v115, v115, v118
	v_mov_b32_e32 v118, 0
	v_readlane_b32 s27, v115, 63
	s_nop 0
	v_mov_b32_dpp v118, v114 row_bcast:15 row_mask:0xa bank_mask:0xf
	v_add_f32_e32 v114, v114, v118
	v_mov_b32_e32 v118, 0
	s_nop 0
	v_lshlrev_b32_e32 v124, 16, v128
	v_mov_b32_dpp v118, v114 row_bcast:31 row_mask:0xc bank_mask:0xf
	v_add_f32_e32 v114, v114, v118
	v_and_b32_e32 v125, 0xffff0000, v128
	v_readlane_b32 s26, v114, 63
	v_mov_b64_e32 v[114:115], s[28:29]
	v_lshlrev_b32_e32 v128, 16, v92
	v_pk_mul_f32 v[118:119], s[26:27], v[114:115] op_sel_hi:[1,0]
	v_and_b32_e32 v129, 0xffff0000, v92
	v_fma_f32 v118, -v119, v119, v118
	v_max_f32_e32 v118, 0, v118
	v_add_f32_e32 v118, 0x358637bd, v118
	v_rsq_f32_e32 v118, v118
	v_sub_f32_e32 v104, v104, v119
	v_lshlrev_b32_e32 v92, 16, v93
	v_and_b32_e32 v93, 0xffff0000, v93
	v_mul_f32_e32 v104, v104, v118
	v_fma_f32 v104, v72, v104, v80
	v_mul_f32_e32 v117, 0xbfb8aa3b, v104
	v_exp_f32_e32 v117, v117
	s_nop 0
	s_nop 0
	s_waitcnt vmcnt(0)
	v_lshlrev_b32_e32 v132, 16, v96
	v_add_f32_e32 v117, 1.0, v117
	v_rcp_f32_e32 v117, v117
	v_and_b32_e32 v133, 0xffff0000, v96
	v_lshlrev_b32_e32 v96, 16, v97
	v_and_b32_e32 v97, 0xffff0000, v97
	v_mul_f32_e32 v117, v104, v117
	v_sub_f32_e32 v104, v105, v119
	v_mul_f32_e32 v104, v104, v118
	v_fma_f32 v104, v73, v104, v81
	v_mul_f32_e32 v105, 0xbfb8aa3b, v104
	v_exp_f32_e32 v105, v105
	s_nop 0
	s_nop 0
	s_nop 0
	v_add_f32_e32 v105, 1.0, v105
	v_rcp_f32_e32 v105, v105
	s_nop 0
	s_nop 0
	v_lshlrev_b32_e32 v130, 16, v94
	v_mul_f32_e32 v140, v104, v105
	v_sub_f32_e32 v104, v106, v119
	v_mul_f32_e32 v104, v104, v118
	v_fma_f32 v104, v74, v104, v82
	v_mul_f32_e32 v105, 0xbfb8aa3b, v104
	v_exp_f32_e32 v105, v105
	v_lshlrev_b32_e32 v94, 16, v95
	v_and_b32_e32 v95, 0xffff0000, v95
	s_nop 0
	v_add_f32_e32 v105, 1.0, v105
	v_rcp_f32_e32 v105, v105
	s_nop 0
	v_lshlrev_b32_e32 v134, 16, v98
	v_and_b32_e32 v135, 0xffff0000, v98
	v_mul_f32_e32 v141, v104, v105
	v_sub_f32_e32 v104, v107, v119
	v_mul_f32_e32 v104, v104, v118
	v_fma_f32 v104, v75, v104, v83
	v_mul_f32_e32 v105, 0xbfb8aa3b, v104
	v_exp_f32_e32 v105, v105
	v_pk_mul_f32 v[106:107], v[54:55], v[122:123]
	v_lshlrev_b32_e32 v98, 16, v99
	v_pk_fma_f32 v[92:93], v[62:63], v[92:93], v[106:107]
	v_add_f32_e32 v105, 1.0, v105
	v_rcp_f32_e32 v105, v105
	v_pk_fma_f32 v[92:93], v[66:67], v[96:97], v[92:93]
	v_and_b32_e32 v99, 0xffff0000, v99
	v_pk_mul_f32 v[92:93], v[88:89], v[92:93]
	v_mul_f32_e32 v142, v104, v105
	v_pk_mul_f32 v[104:105], v[52:53], v[120:121]
	v_pk_fma_f32 v[104:105], v[60:61], v[128:129], v[104:105]
	v_pk_fma_f32 v[96:97], v[64:65], v[132:133], v[104:105]
	v_lshlrev_b32_e32 v138, 16, v90
	v_pk_mul_f32 v[88:89], v[136:137], v[96:97]
	v_sub_f32_e32 v96, v100, v119
	v_mul_f32_e32 v96, v96, v118
	v_fma_f32 v96, v76, v96, v84
	v_mul_f32_e32 v97, 0xbfb8aa3b, v96
	v_exp_f32_e32 v97, v97
	v_and_b32_e32 v139, 0xffff0000, v90
	v_lshlrev_b32_e32 v90, 16, v91
	v_and_b32_e32 v91, 0xffff0000, v91
	v_add_f32_e32 v97, 1.0, v97
	v_rcp_f32_e32 v97, v97
	s_nop 0
	s_nop 0
	s_lshl_b64 s[26:27], s[44:45], 11
	v_mul_f32_e32 v104, v96, v97
	v_sub_f32_e32 v96, v101, v119
	v_mul_f32_e32 v96, v96, v118
	v_fma_f32 v96, v77, v96, v85
	v_mul_f32_e32 v97, 0xbfb8aa3b, v96
	v_exp_f32_e32 v97, v97
	v_pk_mul_f32 v[100:101], v[50:51], v[126:127]
	s_add_i32 s44, s24, 0xffc1
	v_pk_fma_f32 v[94:95], v[58:59], v[94:95], v[100:101]
	v_add_f32_e32 v97, 1.0, v97
	v_rcp_f32_e32 v97, v97
	v_pk_fma_f32 v[94:95], v[70:71], v[98:99], v[94:95]
	v_cvt_pk_bf16_f32 v88, v88, v89
	v_cvt_pk_bf16_f32 v89, v92, v93
	v_mul_f32_e32 v105, v96, v97
	v_sub_f32_e32 v96, v102, v119
	v_mul_f32_e32 v96, v96, v118
	v_fma_f32 v96, v78, v96, v86
	v_mul_f32_e32 v97, 0xbfb8aa3b, v96
	v_exp_f32_e32 v97, v97
	v_pk_mul_f32 v[94:95], v[90:91], v[94:95]
	v_lshl_add_u64 v[92:93], v[112:113], 0, s[26:27]
	s_ashr_i32 s45, s44, 31
	v_add_f32_e32 v97, 1.0, v97
	v_rcp_f32_e32 v97, v97
	s_add_i32 s28, s25, 1
	s_lshl_b64 s[26:27], s[44:45], 10
	s_cmp_gt_i32 s28, 0
	v_mul_f32_e32 v102, v96, v97
	v_sub_f32_e32 v96, v103, v119
	v_mul_f32_e32 v96, v96, v118
	v_fma_f32 v96, v79, v96, v87
	v_mul_f32_e32 v97, 0xbfb8aa3b, v96
	v_exp_f32_e32 v97, v97
	s_nop 0
	v_add_f32_e32 v97, 1.0, v97
	v_rcp_f32_e32 v97, v97
	s_nop 0
	v_mul_f32_e32 v103, v96, v97
	v_pk_mul_f32 v[96:97], v[48:49], v[124:125]
	s_nop 0
	v_pk_fma_f32 v[96:97], v[56:57], v[130:131], v[96:97]
	s_nop 0
	v_pk_fma_f32 v[96:97], v[68:69], v[134:135], v[96:97]
	s_nop 0
	v_pk_mul_f32 v[90:91], v[138:139], v[96:97]
	s_nop 0
	v_cvt_pk_bf16_f32 v90, v90, v91
	v_cvt_pk_bf16_f32 v91, v94, v95
	global_store_dwordx4 v[92:93], v[88:91], off
	s_nop 1
	v_cvt_pk_bf16_f32 v88, v117, v140
	v_cvt_pk_bf16_f32 v89, v141, v142
	v_cvt_pk_bf16_f32 v90, v104, v105
	v_cvt_pk_bf16_f32 v91, v102, v103
	global_store_dwordx4 v[92:93], v[88:91], off offset:1024
	s_nop 1
	v_lshl_add_u64 v[88:89], v[108:109], 0, s[26:27]
	global_load_dwordx4 v[100:103], v[88:89], off
	v_lshl_add_u64 v[88:89], v[110:111], 0, s[26:27]
	s_cselect_b64 s[26:27], -1, 0
	s_cmp_lg_u64 s[26:27], 0
	s_subb_u32 s26, s44, 0
	s_ashr_i32 s27, s26, 31
	s_lshl_b64 s[26:27], s[26:27], 10
	s_cmpk_lt_i32 s28, 0x7ff
	global_load_dwordx4 v[96:99], v[88:89], off
	v_lshl_add_u64 v[88:89], v[108:109], 0, s[26:27]
	s_cselect_b64 s[26:27], -1, 0
	s_cmp_lg_u64 s[26:27], 0
	s_addc_u32 s26, s24, 0xffc1
	s_ashr_i32 s27, s26, 31
	s_lshl_b64 s[26:27], s[26:27], 10
	global_load_dwordx4 v[104:107], v[88:89], off
	v_lshl_add_u64 v[88:89], v[108:109], 0, s[26:27]
	global_load_dwordx4 v[88:91], v[88:89], off
	s_cmpk_lg_i32 s25, 0x7fe
	s_cselect_b64 vcc, -1, 0
	s_add_i32 s46, s46, 2
	s_waitcnt vmcnt(2)
	v_lshlrev_b32_e32 v134, 16, v96
	v_and_b32_e32 v135, 0xffff0000, v96
	v_lshlrev_b32_e32 v96, 16, v97
	v_and_b32_e32 v97, 0xffff0000, v97
	v_lshlrev_b32_e32 v136, 16, v98
	v_and_b32_e32 v137, 0xffff0000, v98
	v_lshlrev_b32_e32 v98, 16, v99
	v_and_b32_e32 v99, 0xffff0000, v99
	s_waitcnt vmcnt(0)
	v_cndmask_b32_e32 v117, 0, v91, vcc
	v_cndmask_b32_e32 v118, 0, v90, vcc
	v_cndmask_b32_e32 v119, 0, v89, vcc
	v_cndmask_b32_e32 v120, 0, v88, vcc
	ds_read_b128 v[92:95], v116 offset:2048
	ds_read_b128 v[88:91], v116 offset:2064
	s_waitcnt lgkmcnt(1)
	v_mov_b32_e32 v122, v92
	s_waitcnt lgkmcnt(0)
	v_mov_b32_e32 v123, v88
	v_mov_b32_e32 v124, v93
	v_mov_b32_e32 v125, v89
	v_pk_add_f32 v[126:127], v[122:123], v[124:125]
	v_mov_b32_e32 v128, v94
	v_mov_b32_e32 v129, v90
	v_mov_b32_e32 v130, v95
	v_mov_b32_e32 v131, v91
	v_pk_mul_f32 v[124:125], v[124:125], v[124:125]
	v_pk_add_f32 v[132:133], v[128:129], v[130:131]
	v_pk_fma_f32 v[122:123], v[122:123], v[122:123], v[124:125]
	v_pk_mul_f32 v[124:125], v[130:131], v[130:131]
	v_pk_add_f32 v[126:127], v[126:127], v[132:133]
	v_pk_fma_f32 v[124:125], v[128:129], v[128:129], v[124:125]
	v_add_f32_e32 v126, v126, v127
	v_pk_add_f32 v[122:123], v[122:123], v[124:125]
	v_lshlrev_b32_e32 v130, 16, v120
	v_add_f32_e32 v121, v122, v123
	v_add_f32_dpp v122, v126, v126 quad_perm:[1,0,3,2] row_mask:0xf bank_mask:0xf bound_ctrl:1
	v_mov_b32_e32 v123, 0
	v_add_f32_dpp v121, v121, v121 quad_perm:[1,0,3,2] row_mask:0xf bank_mask:0xf bound_ctrl:1
	v_add_f32_dpp v122, v122, v122 quad_perm:[2,3,0,1] row_mask:0xf bank_mask:0xf bound_ctrl:1
	v_and_b32_e32 v131, 0xffff0000, v120
	v_add_f32_dpp v121, v121, v121 quad_perm:[2,3,0,1] row_mask:0xf bank_mask:0xf bound_ctrl:1
	v_add_f32_dpp v122, v122, v122 row_shr:4 row_mask:0xf bank_mask:0xf bound_ctrl:1
	v_lshlrev_b32_e32 v120, 16, v119
	v_add_f32_dpp v121, v121, v121 row_shr:4 row_mask:0xf bank_mask:0xf bound_ctrl:1
	v_add_f32_dpp v122, v122, v122 row_shr:8 row_mask:0xf bank_mask:0xf bound_ctrl:1
	v_lshlrev_b32_e32 v132, 16, v118
	v_add_f32_dpp v121, v121, v121 row_shr:8 row_mask:0xf bank_mask:0xf bound_ctrl:1
	v_mov_b32_dpp v123, v122 row_bcast:15 row_mask:0xa bank_mask:0xf
	v_add_f32_e32 v122, v122, v123
	v_mov_b32_e32 v123, 0
	v_and_b32_e32 v133, 0xffff0000, v118
	v_lshlrev_b32_e32 v118, 16, v117
	v_mov_b32_dpp v123, v122 row_bcast:31 row_mask:0xc bank_mask:0xf
	v_add_f32_e32 v122, v122, v123
	v_mov_b32_e32 v123, 0
	v_readlane_b32 s25, v122, 63
	v_lshlrev_b32_e32 v122, 16, v104
	v_mov_b32_dpp v123, v121 row_bcast:15 row_mask:0xa bank_mask:0xf
	v_add_f32_e32 v121, v121, v123
	v_mov_b32_e32 v123, 0
	v_lshlrev_b32_e32 v126, 16, v100
	v_and_b32_e32 v127, 0xffff0000, v100
	v_mov_b32_dpp v123, v121 row_bcast:31 row_mask:0xc bank_mask:0xf
	v_add_f32_e32 v121, v121, v123
	v_and_b32_e32 v123, 0xffff0000, v104
	v_readlane_b32 s24, v121, 63
	v_and_b32_e32 v121, 0xffff0000, v119
	v_and_b32_e32 v119, 0xffff0000, v117
	v_pk_mul_f32 v[114:115], s[24:25], v[114:115] op_sel_hi:[1,0]
	v_lshlrev_b32_e32 v104, 16, v105
	v_fma_f32 v114, -v115, v115, v114
	v_max_f32_e32 v114, 0, v114
	v_add_f32_e32 v114, 0x358637bd, v114
	v_rsq_f32_e32 v114, v114
	v_sub_f32_e32 v92, v92, v115
	v_and_b32_e32 v105, 0xffff0000, v105
	v_mul_f32_e32 v92, v92, v114
	v_fma_f32 v92, v72, v92, v80
	v_mul_f32_e32 v117, 0xbfb8aa3b, v92
	v_exp_f32_e32 v117, v117
	v_lshlrev_b32_e32 v100, 16, v101
	v_and_b32_e32 v101, 0xffff0000, v101
	s_nop 0
	v_add_f32_e32 v117, 1.0, v117
	v_rcp_f32_e32 v117, v117
	v_sub_f32_e32 v88, v88, v115
	s_nop 0
	v_mul_f32_e32 v88, v88, v114
	v_mul_f32_e32 v117, v92, v117
	v_sub_f32_e32 v92, v93, v115
	v_mul_f32_e32 v92, v92, v114
	v_fma_f32 v92, v73, v92, v81
	v_mul_f32_e32 v93, 0xbfb8aa3b, v92
	v_exp_f32_e32 v93, v93
	v_fma_f32 v88, v76, v88, v84
	v_lshlrev_b32_e32 v124, 16, v106
	v_and_b32_e32 v125, 0xffff0000, v106
	v_add_f32_e32 v93, 1.0, v93
	v_rcp_f32_e32 v93, v93
	v_lshlrev_b32_e32 v106, 16, v107
	v_and_b32_e32 v107, 0xffff0000, v107
	v_mul_f32_e32 v138, v92, v93
	v_sub_f32_e32 v92, v94, v115
	v_mul_f32_e32 v92, v92, v114
	v_fma_f32 v92, v74, v92, v82
	v_mul_f32_e32 v93, 0xbfb8aa3b, v92
	v_exp_f32_e32 v93, v93
	v_lshlrev_b32_e32 v128, 16, v102
	v_and_b32_e32 v129, 0xffff0000, v102
	s_nop 0
	v_add_f32_e32 v93, 1.0, v93
	v_rcp_f32_e32 v93, v93
	s_nop 0
	v_lshlrev_b32_e32 v102, 16, v103
	v_and_b32_e32 v103, 0xffff0000, v103
	v_mul_f32_e32 v139, v92, v93
	v_sub_f32_e32 v92, v95, v115
	v_mul_f32_e32 v92, v92, v114
	v_fma_f32 v92, v75, v92, v83
	v_mul_f32_e32 v93, 0xbfb8aa3b, v92
	v_exp_f32_e32 v93, v93
	s_nop 0
	s_nop 0
	s_nop 0
	v_add_f32_e32 v93, 1.0, v93
	v_rcp_f32_e32 v93, v93
	s_nop 0
	v_pk_mul_f32 v[94:95], v[52:53], v[122:123]
	v_mul_f32_e32 v140, v92, v93
	v_pk_mul_f32 v[92:93], v[54:55], v[104:105]
	v_pk_fma_f32 v[92:93], v[62:63], v[100:101], v[92:93]
	v_pk_fma_f32 v[94:95], v[60:61], v[126:127], v[94:95]
	v_pk_fma_f32 v[92:93], v[66:67], v[120:121], v[92:93]
	v_pk_fma_f32 v[94:95], v[64:65], v[130:131], v[94:95]
	v_pk_mul_f32 v[92:93], v[96:97], v[92:93]
	v_mul_f32_e32 v96, 0xbfb8aa3b, v88
	v_exp_f32_e32 v96, v96
	s_lshl_b64 s[24:25], s[44:45], 11
	v_pk_mul_f32 v[94:95], v[134:135], v[94:95]
	v_add_u32_e32 v116, 0x1000, v116
	v_add_f32_e32 v96, 1.0, v96
	v_rcp_f32_e32 v96, v96
	s_cmp_eq_u32 s46, 8
	v_mul_f32_e32 v100, v88, v96
	v_sub_f32_e32 v88, v89, v115
	v_mul_f32_e32 v88, v88, v114
	v_fma_f32 v88, v77, v88, v85
	v_mul_f32_e32 v89, 0xbfb8aa3b, v88
	v_exp_f32_e32 v89, v89
	s_nop 0
	v_add_f32_e32 v89, 1.0, v89
	v_rcp_f32_e32 v89, v89
	s_nop 0
	v_mul_f32_e32 v101, v88, v89
	v_sub_f32_e32 v88, v90, v115
	v_mul_f32_e32 v88, v88, v114
	v_fma_f32 v88, v78, v88, v86
	v_mul_f32_e32 v89, 0xbfb8aa3b, v88
	v_exp_f32_e32 v89, v89
	s_nop 0
	v_add_f32_e32 v89, 1.0, v89
	v_rcp_f32_e32 v89, v89
	s_nop 0
	v_mul_f32_e32 v104, v88, v89
	v_sub_f32_e32 v88, v91, v115
	v_mul_f32_e32 v88, v88, v114
	v_fma_f32 v88, v79, v88, v87
	v_mul_f32_e32 v89, 0xbfb8aa3b, v88
	v_exp_f32_e32 v89, v89
	v_pk_mul_f32 v[90:91], v[48:49], v[124:125]
	v_add_f32_e32 v89, 1.0, v89
	v_rcp_f32_e32 v89, v89
	v_pk_fma_f32 v[90:91], v[56:57], v[128:129], v[90:91]
	v_mul_f32_e32 v105, v88, v89
	v_pk_mul_f32 v[88:89], v[50:51], v[106:107]
	v_pk_fma_f32 v[90:91], v[68:69], v[132:133], v[90:91]
	v_pk_fma_f32 v[88:89], v[58:59], v[102:103], v[88:89]
	v_pk_mul_f32 v[90:91], v[136:137], v[90:91]
	v_pk_fma_f32 v[88:89], v[70:71], v[118:119], v[88:89]
	s_nop 0
	v_pk_mul_f32 v[96:97], v[98:99], v[88:89]
	v_cvt_pk_bf16_f32 v88, v94, v95
	v_cvt_pk_bf16_f32 v89, v92, v93
	v_cvt_pk_bf16_f32 v90, v90, v91
	v_lshl_add_u64 v[92:93], v[112:113], 0, s[24:25]
	v_cvt_pk_bf16_f32 v91, v96, v97
	global_store_dwordx4 v[92:93], v[88:91], off
	s_nop 1
	v_cvt_pk_bf16_f32 v88, v117, v138
	v_cvt_pk_bf16_f32 v89, v139, v140
	v_cvt_pk_bf16_f32 v90, v100, v101
	v_cvt_pk_bf16_f32 v91, v104, v105
	global_store_dwordx4 v[92:93], v[88:91], off offset:1024
	s_cbranch_scc0 .LBB0_549
	s_sub_i32 s19, s19, s86
	s_sub_i32 s6, s6, s86
	s_and_b64 vcc, exec, s[84:85]
	s_cbranch_vccz .LBB0_496

.LBB0_844:
	v_lshl_add_u32 v153, s60, 8, v145
	v_lshl_or_b32 v128, s44, 9, v151
	v_lshl_add_u32 v154, v153, 11, v128
	global_load_dwordx4 v[156:159], v154, s[20:21]
	v_or_b32_e32 v168, 64, v154
	global_load_dwordx4 v[160:163], v168, s[20:21]
	v_add_u32_e32 v169, 0x8000, v154
	global_load_dwordx4 v[132:135], v169, s[20:21]
	v_add_u32_e32 v155, 0x8040, v154
	global_load_dwordx4 v[128:131], v155, s[20:21]
	s_waitcnt vmcnt(0)
	v_lshlrev_b32_e32 v164, 16, v156
	v_and_b32_e32 v165, 0xffff0000, v156
	v_lshlrev_b32_e32 v156, 16, v157
	v_and_b32_e32 v157, 0xffff0000, v157
	v_lshlrev_b32_e32 v166, 16, v158
	v_and_b32_e32 v167, 0xffff0000, v158
	v_lshlrev_b32_e32 v158, 16, v159
	v_and_b32_e32 v159, 0xffff0000, v159
	v_pk_add_f32 v[126:127], v[126:127], v[156:157]
	v_pk_add_f32 v[124:125], v[124:125], v[164:165]
	v_pk_add_f32 v[156:157], v[122:123], v[158:159]
	v_pk_add_f32 v[158:159], v[120:121], v[166:167]
	v_cvt_pk_bf16_f32 v120, v124, v125
	v_cvt_pk_bf16_f32 v121, v126, v127
	s_nop 0
	v_cvt_pk_bf16_f32 v122, v158, v159
	v_cvt_pk_bf16_f32 v123, v156, v157
	global_store_dwordx4 v154, v[120:123], s[20:21]
	s_nop 1
	v_mul_f32_e32 v120, v125, v125
	v_mul_f32_e32 v121, v127, v127
	v_fmac_f32_e32 v120, v124, v124
	v_fmac_f32_e32 v121, v126, v126
	v_add_f32_e32 v120, v120, v121
	v_mul_f32_e32 v121, v159, v159
	v_fmac_f32_e32 v121, v158, v158
	v_add_f32_e32 v120, v121, v120
	v_mul_f32_e32 v121, v157, v157
	v_fmac_f32_e32 v121, v156, v156
	v_add_f32_e32 v156, v121, v120
	v_lshlrev_b32_e32 v120, 16, v160
	v_and_b32_e32 v121, 0xffff0000, v160
	v_lshlrev_b32_e32 v122, 16, v161
	v_and_b32_e32 v123, 0xffff0000, v161
	v_lshlrev_b32_e32 v124, 16, v162
	v_and_b32_e32 v125, 0xffff0000, v162
	v_lshlrev_b32_e32 v126, 16, v163
	v_and_b32_e32 v127, 0xffff0000, v163
	v_pk_add_f32 v[118:119], v[118:119], v[122:123]
	v_pk_add_f32 v[116:117], v[116:117], v[120:121]
	v_pk_add_f32 v[122:123], v[112:113], v[124:125]
	v_cvt_pk_bf16_f32 v112, v116, v117
	v_cvt_pk_bf16_f32 v113, v118, v119
	v_pk_add_f32 v[120:121], v[114:115], v[126:127]
	v_cvt_pk_bf16_f32 v114, v122, v123
	v_lshlrev_b32_e32 v126, 16, v132
	v_cvt_pk_bf16_f32 v115, v120, v121
	global_store_dwordx4 v168, v[112:115], s[20:21]
	v_and_b32_e32 v127, 0xffff0000, v132
	v_lshlrev_b32_e32 v132, 16, v133
	v_mul_f32_e32 v112, v117, v117
	v_mul_f32_e32 v113, v119, v119
	v_fmac_f32_e32 v112, v116, v116
	v_fmac_f32_e32 v113, v118, v118
	v_add_f32_e32 v112, v112, v113
	v_mul_f32_e32 v113, v123, v123
	v_fmac_f32_e32 v113, v122, v122
	v_add_f32_e32 v112, v113, v112
	v_mul_f32_e32 v113, v121, v121
	v_fmac_f32_e32 v113, v120, v120
	v_and_b32_e32 v114, 64, v212
	v_add_f32_e32 v112, v113, v112
	v_xor_b32_e32 v113, 16, v212
	v_add_u32_e32 v114, 64, v114
	v_cmp_lt_i32_e32 vcc, v113, v114
	v_add_f32_e32 v112, v156, v112
	v_and_b32_e32 v133, 0xffff0000, v133
	v_cndmask_b32_e32 v113, v212, v113, vcc
	v_lshlrev_b32_e32 v121, 2, v113
	ds_bpermute_b32 v113, v121, v112
	v_lshlrev_b32_e32 v156, 16, v134
	v_and_b32_e32 v157, 0xffff0000, v134
	v_add_u32_e32 v124, 0x10040, v154
	s_waitcnt lgkmcnt(0)
	v_add_f32_e32 v120, v112, v113
	v_xor_b32_e32 v112, 32, v212
	v_cmp_lt_i32_e32 vcc, v112, v114
	v_add_u32_e32 v125, 0x10000, v154
	s_nop 0
	v_cndmask_b32_e32 v112, v212, v112, vcc
	s_nop 0
	v_lshlrev_b32_e32 v134, 16, v135
	v_and_b32_e32 v135, 0xffff0000, v135
	v_lshlrev_b32_e32 v123, 2, v112
	global_load_dwordx4 v[112:115], v124, s[20:21]
	global_load_dwordx4 v[116:119], v125, s[20:21]
	v_pk_add_f32 v[110:111], v[110:111], v[132:133]
	v_pk_add_f32 v[108:109], v[108:109], v[126:127]
	v_pk_add_f32 v[132:133], v[104:105], v[156:157]
	v_cvt_pk_bf16_f32 v104, v108, v109
	v_cvt_pk_bf16_f32 v105, v110, v111
	v_pk_add_f32 v[126:127], v[106:107], v[134:135]
	v_cvt_pk_bf16_f32 v106, v132, v133
	ds_bpermute_b32 v122, v123, v120
	v_cvt_pk_bf16_f32 v107, v126, v127
	global_store_dwordx4 v169, v[104:107], s[20:21]
	s_nop 1
	v_mul_f32_e32 v104, v109, v109
	v_mul_f32_e32 v105, v111, v111
	v_fmac_f32_e32 v104, v108, v108
	v_fmac_f32_e32 v105, v110, v110
	v_add_f32_e32 v104, v104, v105
	v_mul_f32_e32 v105, v133, v133
	v_fmac_f32_e32 v105, v132, v132
	v_add_f32_e32 v104, v105, v104
	v_mul_f32_e32 v105, v127, v127
	v_fmac_f32_e32 v105, v126, v126
	v_add_f32_e32 v126, v105, v104
	v_lshlrev_b32_e32 v104, 16, v128
	v_and_b32_e32 v105, 0xffff0000, v128
	v_lshlrev_b32_e32 v106, 16, v129
	v_and_b32_e32 v107, 0xffff0000, v129
	v_lshlrev_b32_e32 v108, 16, v130
	v_and_b32_e32 v109, 0xffff0000, v130
	v_lshlrev_b32_e32 v110, 16, v131
	v_and_b32_e32 v111, 0xffff0000, v131
	v_pk_add_f32 v[102:103], v[102:103], v[106:107]
	v_pk_add_f32 v[100:101], v[100:101], v[104:105]
	v_pk_add_f32 v[106:107], v[96:97], v[108:109]
	v_cvt_pk_bf16_f32 v96, v100, v101
	v_cvt_pk_bf16_f32 v97, v102, v103
	v_pk_add_f32 v[104:105], v[98:99], v[110:111]
	v_cvt_pk_bf16_f32 v98, v106, v107
	s_waitcnt vmcnt(1)
	v_lshlrev_b32_e32 v108, 16, v116
	v_cvt_pk_bf16_f32 v99, v104, v105
	global_store_dwordx4 v155, v[96:99], s[20:21]
	v_and_b32_e32 v109, 0xffff0000, v116
	v_lshlrev_b32_e32 v110, 16, v117
	v_mul_f32_e32 v96, v101, v101
	v_mul_f32_e32 v97, v103, v103
	v_fmac_f32_e32 v96, v100, v100
	v_fmac_f32_e32 v97, v102, v102
	v_add_f32_e32 v96, v96, v97
	v_mul_f32_e32 v97, v107, v107
	v_fmac_f32_e32 v97, v106, v106
	v_add_f32_e32 v96, v97, v96
	v_mul_f32_e32 v97, v105, v105
	v_fmac_f32_e32 v97, v104, v104
	v_add_f32_e32 v96, v97, v96
	v_add_f32_e32 v96, v96, v126
	ds_bpermute_b32 v97, v121, v96
	v_add_u32_e32 v102, 0x18040, v154
	v_add_u32_e32 v103, 0x18000, v154
	global_load_dwordx4 v[104:107], v103, s[20:21]
	v_and_b32_e32 v111, 0xffff0000, v117
	s_waitcnt lgkmcnt(0)
	v_add_f32_e32 v100, v96, v97
	global_load_dwordx4 v[96:99], v102, s[20:21]
	v_lshlrev_b32_e32 v116, 16, v118
	v_and_b32_e32 v117, 0xffff0000, v118
	v_lshlrev_b32_e32 v118, 16, v119
	v_and_b32_e32 v119, 0xffff0000, v119
	v_pk_add_f32 v[94:95], v[94:95], v[110:111]
	v_pk_add_f32 v[92:93], v[92:93], v[108:109]
	v_pk_add_f32 v[110:111], v[88:89], v[116:117]
	v_cvt_pk_bf16_f32 v88, v92, v93
	v_cvt_pk_bf16_f32 v89, v94, v95
	v_pk_add_f32 v[108:109], v[90:91], v[118:119]
	v_cvt_pk_bf16_f32 v90, v110, v111
	ds_bpermute_b32 v101, v123, v100
	v_cvt_pk_bf16_f32 v91, v108, v109
	global_store_dwordx4 v125, v[88:91], s[20:21]
	s_nop 1
	v_mul_f32_e32 v88, v93, v93
	v_mul_f32_e32 v89, v95, v95
	v_fmac_f32_e32 v88, v92, v92
	v_fmac_f32_e32 v89, v94, v94
	v_add_f32_e32 v88, v88, v89
	v_mul_f32_e32 v89, v111, v111
	v_fmac_f32_e32 v89, v110, v110
	v_add_f32_e32 v88, v89, v88
	v_mul_f32_e32 v89, v109, v109
	v_fmac_f32_e32 v89, v108, v108
	v_add_f32_e32 v108, v89, v88
	v_lshlrev_b32_e32 v88, 16, v112
	v_and_b32_e32 v89, 0xffff0000, v112
	v_lshlrev_b32_e32 v90, 16, v113
	v_and_b32_e32 v91, 0xffff0000, v113
	v_lshlrev_b32_e32 v92, 16, v114
	v_and_b32_e32 v93, 0xffff0000, v114
	v_lshlrev_b32_e32 v94, 16, v115
	v_and_b32_e32 v95, 0xffff0000, v115
	v_pk_add_f32 v[86:87], v[86:87], v[90:91]
	v_pk_add_f32 v[84:85], v[84:85], v[88:89]
	v_pk_add_f32 v[90:91], v[80:81], v[92:93]
	v_cvt_pk_bf16_f32 v80, v84, v85
	v_cvt_pk_bf16_f32 v81, v86, v87
	v_pk_add_f32 v[88:89], v[82:83], v[94:95]
	v_cvt_pk_bf16_f32 v82, v90, v91
	v_add_u32_e32 v109, 0x40000, v154
	v_cvt_pk_bf16_f32 v83, v88, v89
	global_store_dwordx4 v124, v[80:83], s[20:21]
	s_waitcnt vmcnt(3)
	v_lshlrev_b32_e32 v92, 16, v105
	v_mul_f32_e32 v80, v85, v85
	v_mul_f32_e32 v81, v87, v87
	v_fmac_f32_e32 v80, v84, v84
	v_fmac_f32_e32 v81, v86, v86
	v_add_f32_e32 v80, v80, v81
	v_mul_f32_e32 v81, v91, v91
	v_fmac_f32_e32 v81, v90, v90
	v_add_f32_e32 v80, v81, v80
	v_mul_f32_e32 v81, v89, v89
	v_fmac_f32_e32 v81, v88, v88
	v_add_f32_e32 v80, v81, v80
	v_add_f32_e32 v80, v80, v108
	ds_bpermute_b32 v81, v121, v80
	v_lshlrev_b32_e32 v90, 16, v104
	v_and_b32_e32 v91, 0xffff0000, v104
	v_and_b32_e32 v93, 0xffff0000, v105
	v_lshlrev_b32_e32 v94, 16, v106
	v_and_b32_e32 v95, 0xffff0000, v106
	v_add_u32_e32 v108, 0x40040, v154
	v_lshlrev_b32_e32 v104, 16, v107
	v_and_b32_e32 v105, 0xffff0000, v107
	s_waitcnt lgkmcnt(0)
	v_add_f32_e32 v88, v80, v81
	global_load_dwordx4 v[80:83], v108, s[20:21]
	global_load_dwordx4 v[84:87], v109, s[20:21]
	v_pk_add_f32 v[78:79], v[78:79], v[92:93]
	v_pk_add_f32 v[76:77], v[76:77], v[90:91]
	v_pk_add_f32 v[92:93], v[72:73], v[94:95]
	v_cvt_pk_bf16_f32 v72, v76, v77
	v_cvt_pk_bf16_f32 v73, v78, v79
	v_pk_add_f32 v[90:91], v[74:75], v[104:105]
	v_cvt_pk_bf16_f32 v74, v92, v93
	ds_bpermute_b32 v89, v123, v88
	v_cvt_pk_bf16_f32 v75, v90, v91
	global_store_dwordx4 v103, v[72:75], s[20:21]
	s_nop 1
	v_mul_f32_e32 v72, v77, v77
	v_mul_f32_e32 v73, v79, v79
	v_fmac_f32_e32 v72, v76, v76
	v_fmac_f32_e32 v73, v78, v78
	v_add_f32_e32 v72, v72, v73
	v_mul_f32_e32 v73, v93, v93
	v_fmac_f32_e32 v73, v92, v92
	v_add_f32_e32 v72, v73, v72
	v_mul_f32_e32 v73, v91, v91
	v_fmac_f32_e32 v73, v90, v90
	v_add_f32_e32 v90, v73, v72
	s_waitcnt vmcnt(5)
	v_lshlrev_b32_e32 v72, 16, v96
	v_and_b32_e32 v73, 0xffff0000, v96
	v_lshlrev_b32_e32 v74, 16, v97
	v_and_b32_e32 v75, 0xffff0000, v97
	v_lshlrev_b32_e32 v76, 16, v98
	v_and_b32_e32 v77, 0xffff0000, v98
	v_lshlrev_b32_e32 v78, 16, v99
	v_and_b32_e32 v79, 0xffff0000, v99
	v_pk_add_f32 v[70:71], v[70:71], v[74:75]
	v_pk_add_f32 v[68:69], v[68:69], v[72:73]
	v_pk_add_f32 v[74:75], v[64:65], v[76:77]
	v_cvt_pk_bf16_f32 v64, v68, v69
	v_cvt_pk_bf16_f32 v65, v70, v71
	v_pk_add_f32 v[72:73], v[66:67], v[78:79]
	v_cvt_pk_bf16_f32 v66, v74, v75
	v_add_u32_e32 v91, 0x48000, v154
	v_cvt_pk_bf16_f32 v67, v72, v73
	global_store_dwordx4 v102, v[64:67], s[20:21]
	s_waitcnt vmcnt(2)
	v_lshlrev_b32_e32 v76, 16, v85
	v_mul_f32_e32 v64, v69, v69
	v_mul_f32_e32 v65, v71, v71
	v_fmac_f32_e32 v64, v68, v68
	v_fmac_f32_e32 v65, v70, v70
	v_add_f32_e32 v64, v64, v65
	v_mul_f32_e32 v65, v75, v75
	v_fmac_f32_e32 v65, v74, v74
	v_add_f32_e32 v64, v65, v64
	v_mul_f32_e32 v65, v73, v73
	v_fmac_f32_e32 v65, v72, v72
	v_add_f32_e32 v64, v65, v64
	v_add_f32_e32 v64, v64, v90
	ds_bpermute_b32 v65, v121, v64
	v_add_u32_e32 v90, 0x48040, v154
	global_load_dwordx4 v[70:73], v91, s[20:21]
	v_lshlrev_b32_e32 v74, 16, v84
	v_and_b32_e32 v75, 0xffff0000, v84
	s_waitcnt lgkmcnt(0)
	v_add_f32_e32 v68, v64, v65
	global_load_dwordx4 v[64:67], v90, s[20:21]
	v_and_b32_e32 v77, 0xffff0000, v85
	v_lshlrev_b32_e32 v78, 16, v86
	v_and_b32_e32 v79, 0xffff0000, v86
	v_lshlrev_b32_e32 v84, 16, v87
	v_and_b32_e32 v85, 0xffff0000, v87
	v_pk_add_f32 v[62:63], v[62:63], v[76:77]
	v_pk_add_f32 v[60:61], v[60:61], v[74:75]
	v_pk_add_f32 v[76:77], v[56:57], v[78:79]
	v_cvt_pk_bf16_f32 v56, v60, v61
	v_cvt_pk_bf16_f32 v57, v62, v63
	v_pk_add_f32 v[74:75], v[58:59], v[84:85]
	v_cvt_pk_bf16_f32 v58, v76, v77
	ds_bpermute_b32 v69, v123, v68
	v_cvt_pk_bf16_f32 v59, v74, v75
	global_store_dwordx4 v109, v[56:59], s[20:21]
	s_nop 1
	v_mul_f32_e32 v56, v61, v61
	v_mul_f32_e32 v57, v63, v63
	v_fmac_f32_e32 v56, v60, v60
	v_fmac_f32_e32 v57, v62, v62
	v_add_f32_e32 v56, v56, v57
	v_mul_f32_e32 v57, v77, v77
	v_fmac_f32_e32 v57, v76, v76
	v_add_f32_e32 v56, v57, v56
	v_mul_f32_e32 v57, v75, v75
	v_fmac_f32_e32 v57, v74, v74
	v_add_f32_e32 v74, v57, v56
	v_lshlrev_b32_e32 v56, 16, v80
	v_and_b32_e32 v57, 0xffff0000, v80
	v_lshlrev_b32_e32 v58, 16, v81
	v_and_b32_e32 v59, 0xffff0000, v81
	v_lshlrev_b32_e32 v60, 16, v82
	v_and_b32_e32 v61, 0xffff0000, v82
	v_lshlrev_b32_e32 v62, 16, v83
	v_and_b32_e32 v63, 0xffff0000, v83
	v_pk_add_f32 v[54:55], v[54:55], v[58:59]
	v_pk_add_f32 v[52:53], v[52:53], v[56:57]
	v_pk_add_f32 v[58:59], v[48:49], v[60:61]
	v_cvt_pk_bf16_f32 v48, v52, v53
	v_cvt_pk_bf16_f32 v49, v54, v55
	v_pk_add_f32 v[56:57], v[50:51], v[62:63]
	v_cvt_pk_bf16_f32 v50, v58, v59
	v_add_u32_e32 v75, 0x50000, v154
	v_cvt_pk_bf16_f32 v51, v56, v57
	global_store_dwordx4 v108, v[48:51], s[20:21]
	s_waitcnt vmcnt(3)
	v_lshlrev_b32_e32 v60, 16, v71
	v_mul_f32_e32 v48, v53, v53
	v_mul_f32_e32 v49, v55, v55
	v_fmac_f32_e32 v48, v52, v52
	v_fmac_f32_e32 v49, v54, v54
	v_add_f32_e32 v48, v48, v49
	v_mul_f32_e32 v49, v59, v59
	v_fmac_f32_e32 v49, v58, v58
	v_add_f32_e32 v48, v49, v48
	v_mul_f32_e32 v49, v57, v57
	v_fmac_f32_e32 v49, v56, v56
	v_add_f32_e32 v48, v49, v48
	v_add_f32_e32 v48, v48, v74
	ds_bpermute_b32 v49, v121, v48
	v_lshlrev_b32_e32 v58, 16, v70
	v_and_b32_e32 v59, 0xffff0000, v70
	v_and_b32_e32 v61, 0xffff0000, v71
	v_lshlrev_b32_e32 v62, 16, v72
	v_and_b32_e32 v63, 0xffff0000, v72
	v_add_u32_e32 v74, 0x50040, v154
	v_lshlrev_b32_e32 v70, 16, v73
	v_and_b32_e32 v71, 0xffff0000, v73
	s_waitcnt lgkmcnt(0)
	v_add_f32_e32 v52, v48, v49
	global_load_dwordx4 v[48:51], v74, s[20:21]
	global_load_dwordx4 v[54:57], v75, s[20:21]
	v_pk_add_f32 v[46:47], v[46:47], v[60:61]
	v_pk_add_f32 v[44:45], v[44:45], v[58:59]
	v_pk_add_f32 v[60:61], v[40:41], v[62:63]
	v_cvt_pk_bf16_f32 v40, v44, v45
	v_cvt_pk_bf16_f32 v41, v46, v47
	v_pk_add_f32 v[58:59], v[42:43], v[70:71]
	v_cvt_pk_bf16_f32 v42, v60, v61
	ds_bpermute_b32 v53, v123, v52
	v_cvt_pk_bf16_f32 v43, v58, v59
	global_store_dwordx4 v91, v[40:43], s[20:21]
	s_nop 1
	v_mul_f32_e32 v40, v45, v45
	v_mul_f32_e32 v41, v47, v47
	v_fmac_f32_e32 v40, v44, v44
	v_fmac_f32_e32 v41, v46, v46
	v_add_f32_e32 v40, v40, v41
	v_mul_f32_e32 v41, v61, v61
	v_fmac_f32_e32 v41, v60, v60
	v_add_f32_e32 v40, v41, v40
	v_mul_f32_e32 v41, v59, v59
	v_fmac_f32_e32 v41, v58, v58
	v_add_f32_e32 v58, v41, v40
	s_waitcnt vmcnt(5)
	v_lshlrev_b32_e32 v40, 16, v64
	v_and_b32_e32 v41, 0xffff0000, v64
	v_lshlrev_b32_e32 v42, 16, v65
	v_and_b32_e32 v43, 0xffff0000, v65
	v_lshlrev_b32_e32 v44, 16, v66
	v_and_b32_e32 v45, 0xffff0000, v66
	v_lshlrev_b32_e32 v46, 16, v67
	v_and_b32_e32 v47, 0xffff0000, v67
	v_pk_add_f32 v[38:39], v[38:39], v[42:43]
	v_pk_add_f32 v[36:37], v[36:37], v[40:41]
	v_pk_add_f32 v[42:43], v[32:33], v[44:45]
	v_cvt_pk_bf16_f32 v32, v36, v37
	v_cvt_pk_bf16_f32 v33, v38, v39
	v_pk_add_f32 v[40:41], v[34:35], v[46:47]
	v_cvt_pk_bf16_f32 v34, v42, v43
	v_add_u32_e32 v59, 0x58000, v154
	v_cvt_pk_bf16_f32 v35, v40, v41
	global_store_dwordx4 v90, v[32:35], s[20:21]
	s_waitcnt vmcnt(2)
	v_lshlrev_b32_e32 v44, 16, v55
	v_mul_f32_e32 v32, v37, v37
	v_mul_f32_e32 v33, v39, v39
	v_fmac_f32_e32 v32, v36, v36
	v_fmac_f32_e32 v33, v38, v38
	v_add_f32_e32 v32, v32, v33
	v_mul_f32_e32 v33, v43, v43
	v_fmac_f32_e32 v33, v42, v42
	v_add_f32_e32 v32, v33, v32
	v_mul_f32_e32 v33, v41, v41
	v_fmac_f32_e32 v33, v40, v40
	v_add_f32_e32 v32, v33, v32
	v_add_f32_e32 v32, v32, v58
	ds_bpermute_b32 v33, v121, v32
	v_add_u32_e32 v58, 0x58040, v154
	global_load_dwordx4 v[38:41], v59, s[20:21]
	v_lshlrev_b32_e32 v42, 16, v54
	v_and_b32_e32 v43, 0xffff0000, v54
	s_waitcnt lgkmcnt(0)
	v_add_f32_e32 v36, v32, v33
	global_load_dwordx4 v[32:35], v58, s[20:21]
	v_and_b32_e32 v45, 0xffff0000, v55
	v_lshlrev_b32_e32 v46, 16, v56
	v_and_b32_e32 v47, 0xffff0000, v56
	v_lshlrev_b32_e32 v54, 16, v57
	v_and_b32_e32 v55, 0xffff0000, v57
	v_pk_add_f32 v[30:31], v[30:31], v[44:45]
	v_pk_add_f32 v[28:29], v[28:29], v[42:43]
	v_pk_add_f32 v[44:45], v[24:25], v[46:47]
	v_cvt_pk_bf16_f32 v24, v28, v29
	v_cvt_pk_bf16_f32 v25, v30, v31
	v_pk_add_f32 v[42:43], v[26:27], v[54:55]
	v_cvt_pk_bf16_f32 v26, v44, v45
	ds_bpermute_b32 v37, v123, v36
	v_cvt_pk_bf16_f32 v27, v42, v43
	global_store_dwordx4 v75, v[24:27], s[20:21]
	s_nop 1
	v_mul_f32_e32 v24, v29, v29
	v_mul_f32_e32 v25, v31, v31
	v_fmac_f32_e32 v24, v28, v28
	v_fmac_f32_e32 v25, v30, v30
	v_add_f32_e32 v24, v24, v25
	v_mul_f32_e32 v25, v45, v45
	v_fmac_f32_e32 v25, v44, v44
	v_add_f32_e32 v24, v25, v24
	v_mul_f32_e32 v25, v43, v43
	v_fmac_f32_e32 v25, v42, v42
	v_add_f32_e32 v42, v25, v24
	v_lshlrev_b32_e32 v24, 16, v48
	v_and_b32_e32 v25, 0xffff0000, v48
	v_lshlrev_b32_e32 v26, 16, v49
	v_and_b32_e32 v27, 0xffff0000, v49
	v_lshlrev_b32_e32 v28, 16, v50
	v_and_b32_e32 v29, 0xffff0000, v50
	v_lshlrev_b32_e32 v30, 16, v51
	v_and_b32_e32 v31, 0xffff0000, v51
	v_pk_add_f32 v[22:23], v[22:23], v[26:27]
	v_pk_add_f32 v[20:21], v[20:21], v[24:25]
	v_pk_add_f32 v[26:27], v[16:17], v[28:29]
	v_cvt_pk_bf16_f32 v16, v20, v21
	v_cvt_pk_bf16_f32 v17, v22, v23
	v_pk_add_f32 v[24:25], v[18:19], v[30:31]
	v_cvt_pk_bf16_f32 v18, v26, v27
	s_nop 0
	v_cvt_pk_bf16_f32 v19, v24, v25
	global_store_dwordx4 v74, v[16:19], s[20:21]
	s_nop 1
	v_mul_f32_e32 v16, v21, v21
	v_mul_f32_e32 v17, v23, v23
	v_fmac_f32_e32 v16, v20, v20
	v_fmac_f32_e32 v17, v22, v22
	v_add_f32_e32 v16, v16, v17
	v_mul_f32_e32 v17, v27, v27
	v_fmac_f32_e32 v17, v26, v26
	v_add_f32_e32 v16, v17, v16
	v_mul_f32_e32 v17, v25, v25
	v_fmac_f32_e32 v17, v24, v24
	v_add_f32_e32 v16, v17, v16
	v_add_f32_e32 v16, v16, v42
	ds_bpermute_b32 v17, v121, v16
	s_waitcnt lgkmcnt(0)
	v_add_f32_e32 v16, v16, v17
	s_waitcnt vmcnt(3)
	v_lshlrev_b32_e32 v18, 16, v38
	v_and_b32_e32 v19, 0xffff0000, v38
	v_lshlrev_b32_e32 v20, 16, v39
	v_and_b32_e32 v21, 0xffff0000, v39
	v_lshlrev_b32_e32 v22, 16, v40
	v_and_b32_e32 v23, 0xffff0000, v40
	v_lshlrev_b32_e32 v24, 16, v41
	v_and_b32_e32 v25, 0xffff0000, v41
	v_pk_add_f32 v[14:15], v[14:15], v[20:21]
	v_pk_add_f32 v[12:13], v[12:13], v[18:19]
	v_pk_add_f32 v[20:21], v[8:9], v[22:23]
	v_cvt_pk_bf16_f32 v8, v12, v13
	v_cvt_pk_bf16_f32 v9, v14, v15
	v_pk_add_f32 v[18:19], v[10:11], v[24:25]
	v_cvt_pk_bf16_f32 v10, v20, v21
	ds_bpermute_b32 v17, v123, v16
	v_cvt_pk_bf16_f32 v11, v18, v19
	global_store_dwordx4 v59, v[8:11], s[20:21]
	s_nop 1
	v_mul_f32_e32 v8, v13, v13
	v_mul_f32_e32 v9, v15, v15
	v_fmac_f32_e32 v8, v12, v12
	v_fmac_f32_e32 v9, v14, v14
	v_add_f32_e32 v8, v8, v9
	v_mul_f32_e32 v9, v21, v21
	v_fmac_f32_e32 v9, v20, v20
	v_add_f32_e32 v8, v9, v8
	v_mul_f32_e32 v9, v19, v19
	v_fmac_f32_e32 v9, v18, v18
	v_add_f32_e32 v18, v9, v8
	s_waitcnt vmcnt(3)
	v_lshlrev_b32_e32 v8, 16, v32
	v_and_b32_e32 v9, 0xffff0000, v32
	v_lshlrev_b32_e32 v10, 16, v33
	v_and_b32_e32 v11, 0xffff0000, v33
	v_lshlrev_b32_e32 v12, 16, v34
	v_and_b32_e32 v13, 0xffff0000, v34
	v_lshlrev_b32_e32 v14, 16, v35
	v_and_b32_e32 v15, 0xffff0000, v35
	v_pk_add_f32 v[6:7], v[6:7], v[10:11]
	v_pk_add_f32 v[4:5], v[4:5], v[8:9]
	v_pk_add_f32 v[10:11], v[0:1], v[12:13]
	v_cvt_pk_bf16_f32 v0, v4, v5
	v_cvt_pk_bf16_f32 v1, v6, v7
	v_pk_add_f32 v[8:9], v[2:3], v[14:15]
	v_cvt_pk_bf16_f32 v2, v10, v11
	s_nop 0
	v_cvt_pk_bf16_f32 v3, v8, v9
	global_store_dwordx4 v58, v[0:3], s[20:21]
	s_nop 1
	v_mul_f32_e32 v0, v5, v5
	v_mul_f32_e32 v1, v7, v7
	v_fmac_f32_e32 v0, v4, v4
	v_fmac_f32_e32 v1, v6, v6
	v_add_f32_e32 v0, v0, v1
	v_mul_f32_e32 v1, v11, v11
	v_fmac_f32_e32 v1, v10, v10
	v_add_f32_e32 v0, v1, v0
	v_mul_f32_e32 v1, v9, v9
	v_fmac_f32_e32 v1, v8, v8
	v_add_f32_e32 v0, v1, v0
	v_add_f32_e32 v0, v0, v18
	ds_bpermute_b32 v1, v121, v0
	s_waitcnt lgkmcnt(0)
	v_add_f32_e32 v0, v0, v1
	ds_bpermute_b32 v1, v123, v0
	s_and_saveexec_b64 s[60:61], s[42:43]
	s_cbranch_execz .LBB0_846
	s_lshl_b32 s24, s44, 4
	s_or_b32 s24, s24, s81
	v_add_f32_e32 v8, v120, v122
	s_waitcnt lgkmcnt(0)
	v_add_f32_e32 v0, v0, v1
	v_lshl_add_u32 v1, v153, 6, s24
	v_add_f32_e32 v7, v100, v101
	global_store_dword v1, v8, s[4:5]
	v_add_u32_e32 v8, 0x400, v1
	v_add_f32_e32 v6, v88, v89
	global_store_dword v8, v7, s[4:5]
	v_add_u32_e32 v7, 0x800, v1
	v_add_f32_e32 v5, v68, v69
	global_store_dword v7, v6, s[4:5]
	v_add_u32_e32 v6, 0xc00, v1
	v_add_f32_e32 v4, v52, v53
	global_store_dword v6, v5, s[4:5]
	v_add_u32_e32 v5, 0x2000, v1
	v_add_f32_e32 v3, v36, v37
	global_store_dword v5, v4, s[4:5]
	v_add_u32_e32 v4, 0x2400, v1
	v_add_f32_e32 v2, v16, v17
	global_store_dword v4, v3, s[4:5]
	v_add_u32_e32 v3, 0x2800, v1
	v_add_u32_e32 v1, 0x2c00, v1
	global_store_dword v3, v2, s[4:5]
	global_store_dword v1, v0, s[4:5]

.LBB0_918:
	s_ashr_i32 s3, s2, 31
	s_lshl_b64 s[0:1], s[2:3], 6
	s_add_u32 s0, s4, s0
	s_addc_u32 s1, s5, s1
	global_load_dwordx4 v[22:25], v17, s[0:1]
	global_load_dwordx4 v[26:29], v17, s[0:1] offset:16
	global_load_dwordx4 v[30:33], v17, s[0:1] offset:32
	global_load_dwordx4 v[34:37], v17, s[0:1] offset:48
	s_lshl_b64 s[0:1], s[2:3], 11
	v_lshl_add_u64 v[42:43], v[18:19], 0, s[0:1]
	s_add_i32 s0, s2, s10
	s_ashr_i32 s1, s0, 31
	s_lshl_b64 s[6:7], s[0:1], 6
	global_load_dwordx4 v[38:41], v[42:43], off
	s_nop 0
	global_load_dwordx4 v[42:45], v[42:43], off offset:1024
	s_add_u32 s6, s4, s6
	s_addc_u32 s7, s5, s7
	global_load_dwordx4 v[46:49], v17, s[6:7]
	global_load_dwordx4 v[50:53], v17, s[6:7] offset:16
	global_load_dwordx4 v[54:57], v17, s[6:7] offset:32
	global_load_dwordx4 v[58:61], v17, s[6:7] offset:48
	s_lshl_b64 s[6:7], s[0:1], 11
	v_lshl_add_u64 v[66:67], v[18:19], 0, s[6:7]
	global_load_dwordx4 v[62:65], v[66:67], off
	s_lshl_b64 s[2:3], s[2:3], 12
	global_load_dwordx4 v[66:69], v[66:67], off offset:1024
	v_lshl_add_u64 v[70:71], v[20:21], 0, s[2:3]
	s_lshl_b64 s[2:3], s[0:1], 12
	s_waitcnt vmcnt(10)
	v_pk_add_f32 v[24:25], v[24:25], v[28:29]
	v_pk_add_f32 v[22:23], v[22:23], v[26:27]
	s_waitcnt vmcnt(8)
	v_pk_add_f32 v[26:27], v[32:33], v[36:37]
	v_pk_add_f32 v[28:29], v[30:31], v[34:35]
	v_pk_add_f32 v[24:25], v[24:25], v[26:27]
	v_pk_add_f32 v[22:23], v[22:23], v[28:29]
	s_waitcnt vmcnt(7)
	v_lshlrev_b32_e32 v28, 16, v39
	s_waitcnt vmcnt(6)
	v_lshlrev_b32_e32 v34, 16, v42
	v_and_b32_e32 v35, 0xffff0000, v42
	v_lshlrev_b32_e32 v36, 16, v43
	v_and_b32_e32 v37, 0xffff0000, v43
	v_mov_b32_e32 v42, v23
	v_mov_b32_e32 v43, v24
	v_mov_b32_e32 v23, v25
	v_and_b32_e32 v29, 0xffff0000, v39
	v_lshlrev_b32_e32 v30, 16, v40
	v_and_b32_e32 v31, 0xffff0000, v40
	v_lshlrev_b32_e32 v32, 16, v41
	v_and_b32_e32 v33, 0xffff0000, v41
	v_lshlrev_b32_e32 v40, 16, v45
	v_and_b32_e32 v41, 0xffff0000, v45
	v_pk_add_f32 v[22:23], v[42:43], v[22:23]
	v_lshlrev_b32_e32 v26, 16, v38
	v_and_b32_e32 v27, 0xffff0000, v38
	v_lshlrev_b32_e32 v38, 16, v44
	v_and_b32_e32 v39, 0xffff0000, v44
	v_pk_add_f32 v[24:25], v[28:29], 0 op_sel_hi:[1,0]
	v_pk_add_f32 v[28:29], v[32:33], 0 op_sel_hi:[1,0]
	v_pk_add_f32 v[32:33], v[36:37], 0 op_sel_hi:[1,0]
	v_pk_add_f32 v[36:37], v[40:41], 0 op_sel_hi:[1,0]
	v_add_f32_e32 v72, v22, v23
	s_waitcnt vmcnt(4)
	v_pk_add_f32 v[22:23], v[48:49], v[52:53]
	v_pk_add_f32 v[40:41], v[46:47], v[50:51]
	s_waitcnt vmcnt(2)
	v_pk_add_f32 v[42:43], v[56:57], v[60:61]
	v_pk_add_f32 v[44:45], v[54:55], v[58:59]
	v_fmamk_f32 v46, v72, 0x3a800000, v16
	v_pk_add_f32 v[22:23], v[22:23], v[42:43]
	v_pk_add_f32 v[40:41], v[40:41], v[44:45]
	v_rsq_f32_e32 v42, v46
	v_mov_b32_e32 v44, v41
	v_mov_b32_e32 v45, v22
	v_mov_b32_e32 v41, v23
	v_pk_add_f32 v[22:23], v[44:45], v[40:41]
	v_add_f32_e32 v22, v22, v23
	v_fmamk_f32 v22, v22, 0x3a800000, v16
	s_nop 0
	s_nop 0
	v_rsq_f32_e32 v40, v22
	v_pk_mul_f32 v[22:23], v[26:27], v[42:43] op_sel_hi:[1,0]
	v_pk_mul_f32 v[24:25], v[24:25], v[42:43] op_sel_hi:[1,0]
	v_pk_mul_f32 v[26:27], v[30:31], v[42:43] op_sel_hi:[1,0]
	v_pk_mul_f32 v[28:29], v[28:29], v[42:43] op_sel_hi:[1,0]
	v_pk_mul_f32 v[30:31], v[42:43], v[34:35] op_sel_hi:[0,1]
	v_pk_mul_f32 v[32:33], v[42:43], v[32:33] op_sel_hi:[0,1]
	v_pk_mul_f32 v[34:35], v[42:43], v[38:39] op_sel_hi:[0,1]
	v_pk_mul_f32 v[36:37], v[42:43], v[36:37] op_sel_hi:[0,1]
	v_pk_mul_f32 v[24:25], v[6:7], v[24:25]
	v_pk_mul_f32 v[22:23], v[4:5], v[22:23]
	v_pk_mul_f32 v[28:29], v[2:3], v[28:29]
	v_pk_mul_f32 v[26:27], v[0:1], v[26:27]
	v_pk_mul_f32 v[32:33], v[14:15], v[32:33]
	v_pk_mul_f32 v[30:31], v[12:13], v[30:31]
	v_pk_mul_f32 v[36:37], v[10:11], v[36:37]
	v_pk_mul_f32 v[34:35], v[8:9], v[34:35]
	global_store_dwordx4 v[70:71], v[22:25], off
	global_store_dwordx4 v[70:71], v[26:29], off offset:16
	global_store_dwordx4 v[70:71], v[30:33], off offset:2048
	global_store_dwordx4 v[70:71], v[34:37], off offset:2064
	s_waitcnt vmcnt(5)
	v_lshlrev_b32_e32 v22, 16, v62
	v_and_b32_e32 v23, 0xffff0000, v62
	v_lshlrev_b32_e32 v24, 16, v63
	v_and_b32_e32 v25, 0xffff0000, v63
	v_lshlrev_b32_e32 v28, 16, v64
	v_and_b32_e32 v29, 0xffff0000, v64
	v_lshlrev_b32_e32 v30, 16, v65
	v_and_b32_e32 v31, 0xffff0000, v65
	v_pk_mul_f32 v[22:23], v[22:23], v[40:41] op_sel_hi:[1,0]
	v_pk_mul_f32 v[24:25], v[24:25], v[40:41] op_sel_hi:[1,0]
	v_lshl_add_u64 v[26:27], v[20:21], 0, s[2:3]
	v_pk_mul_f32 v[24:25], v[6:7], v[24:25]
	v_pk_mul_f32 v[22:23], v[4:5], v[22:23]
	global_store_dwordx4 v[26:27], v[22:25], off
	s_add_i32 s2, s0, s10
	s_cmp_lt_i32 s2, 0x10000
	v_pk_mul_f32 v[22:23], v[28:29], v[40:41] op_sel_hi:[1,0]
	v_pk_mul_f32 v[24:25], v[30:31], v[40:41] op_sel_hi:[1,0]
	v_pk_mul_f32 v[22:23], v[0:1], v[22:23]
	v_pk_mul_f32 v[24:25], v[2:3], v[24:25]
	global_store_dwordx4 v[26:27], v[22:25], off offset:16
	s_waitcnt vmcnt(6)
	v_lshlrev_b32_e32 v28, 16, v68
	v_and_b32_e32 v29, 0xffff0000, v68
	v_lshlrev_b32_e32 v22, 16, v66
	v_and_b32_e32 v23, 0xffff0000, v66
	v_lshlrev_b32_e32 v24, 16, v67
	v_and_b32_e32 v25, 0xffff0000, v67
	v_lshlrev_b32_e32 v30, 16, v69
	v_and_b32_e32 v31, 0xffff0000, v69
	v_pk_mul_f32 v[22:23], v[40:41], v[22:23] op_sel_hi:[0,1]
	v_pk_mul_f32 v[24:25], v[40:41], v[24:25] op_sel_hi:[0,1]
	v_pk_mul_f32 v[24:25], v[14:15], v[24:25]
	v_pk_mul_f32 v[22:23], v[12:13], v[22:23]
	global_store_dwordx4 v[26:27], v[22:25], off offset:2048
	s_nop 1
	v_pk_mul_f32 v[22:23], v[40:41], v[28:29] op_sel_hi:[0,1]
	v_pk_mul_f32 v[24:25], v[40:41], v[30:31] op_sel_hi:[0,1]
	v_pk_mul_f32 v[24:25], v[10:11], v[24:25]
	v_pk_mul_f32 v[22:23], v[8:9], v[22:23]
	global_store_dwordx4 v[26:27], v[22:25], off offset:2064
	s_cbranch_scc1 .LBB0_918
